# GEMM K-loops: B tile of step k+2 issued right after the step barrier (into the slot A_k vacated) instead of in the next step's first MFMA groups
# baseline (speedup 1.0000x reference)
.LBB0_71:
	s_ashr_i32 s36, s31, 2
	s_and_b32 s36, s36, -8
	s_or_b32 s36, s36, s3
	s_ashr_i32 s37, s36, 31
	s_lshr_b32 s37, s37, 29
	s_add_i32 s37, s36, s37
	s_ashr_i32 s43, s37, 3
	s_and_b32 s37, s37, 0x1ffff8
	s_bfe_u32 s5, s31, 0x20003
	s_sub_i32 s42, s36, s37
	s_lshl_b32 s37, s43, 2
	s_lshl_b32 s33, s5, 8
	s_or_b32 s37, s37, s5
	s_lshl_b32 s5, s42, 11
	s_lshl_b32 s42, s31, 8
	s_and_b32 s42, s42, 0x700
	s_or_b32 s42, s5, s42
	v_add_u32_e32 v0, s42, v187
	v_ashrrev_i32_e32 v1, 31, v0
	v_lshl_add_u32 v2, s37, 8, v187
	v_lshlrev_b64 v[0:1], 12, v[0:1]
	v_ashrrev_i32_e32 v3, 31, v2
	v_readfirstlane_b32 s5, v188
	v_lshl_add_u64 v[0:1], v[146:147], 0, v[0:1]
	v_lshlrev_b64 v[2:3], 12, v[2:3]
	s_add_i32 m0, s5, -16
	v_readfirstlane_b32 s5, v200
	v_lshl_add_u64 v[2:3], v[148:149], 0, v[2:3]
	global_load_lds_dwordx4 v[0:1], off
	s_add_i32 m0, s5, -16
	v_readfirstlane_b32 s5, v201
	global_load_lds_dwordx4 v[2:3], off
	v_lshl_add_u64 v[4:5], v[0:1], 0, s[6:7]
	s_add_i32 m0, s5, -16
	v_readfirstlane_b32 s5, v202
	global_load_lds_dwordx4 v[4:5], off
	v_lshl_add_u64 v[4:5], v[2:3], 0, s[6:7]
	s_add_i32 m0, s5, -16
	v_readfirstlane_b32 s5, v203
	global_load_lds_dwordx4 v[4:5], off
	v_lshl_add_u64 v[4:5], v[0:1], 0, s[14:15]
	s_add_i32 m0, s5, -16
	v_readfirstlane_b32 s5, v204
	global_load_lds_dwordx4 v[4:5], off
	v_lshl_add_u64 v[4:5], v[2:3], 0, s[14:15]
	s_add_i32 m0, s5, -16
	v_readfirstlane_b32 s5, v205
	global_load_lds_dwordx4 v[4:5], off
	v_lshl_add_u64 v[0:1], v[0:1], 0, s[20:21]
	s_add_i32 m0, s5, -16
	v_readfirstlane_b32 s5, v206
	global_load_lds_dwordx4 v[0:1], off
	v_lshl_add_u64 v[0:1], v[2:3], 0, s[20:21]
	s_add_i32 m0, s5, -16
	s_and_b32 s4, s35, 0x700
	global_load_lds_dwordx4 v[0:1], off
	s_lshl_b32 s5, s36, 11
	s_or_b32 s4, s4, s5
	v_add_u32_e32 v0, s4, v187
	s_lshl_b32 s4, s43, 14
	v_subrev_u32_e32 v0, s4, v0
	v_ashrrev_i32_e32 v1, 31, v0
	s_lshl_b32 s4, s43, 10
	v_lshlrev_b64 v[0:1], 12, v[0:1]
	s_or_b32 s4, s33, s4
	v_lshl_add_u64 v[128:129], v[158:159], 0, v[0:1]
	v_add_u32_e32 v0, s4, v187
	v_ashrrev_i32_e32 v1, 31, v0
	v_lshlrev_b64 v[0:1], 12, v[0:1]
	v_lshl_add_u64 v[130:131], v[160:161], 0, v[0:1]
	s_mov_b64 s[4:5], 0
	s_mov_b32 s43, 0
	v_mov_b32_e32 v0, 0
	v_mov_b32_e32 v1, v145
	v_mov_b32_e32 v2, v145
	v_mov_b32_e32 v3, v145
	v_mov_b32_e32 v4, v145
	v_mov_b32_e32 v5, v145
	v_mov_b32_e32 v6, v145
	v_mov_b32_e32 v7, v145
	s_waitcnt vmcnt(0)
	v_mov_b32_e32 v8, v145
	v_mov_b32_e32 v9, v145
	v_mov_b32_e32 v10, v145
	v_mov_b32_e32 v11, v145
	v_mov_b32_e32 v12, v145
	v_mov_b32_e32 v13, v145
	v_mov_b32_e32 v14, v145
	v_mov_b32_e32 v15, v145
	v_mov_b32_e32 v16, 0
	v_mov_b32_e32 v17, v145
	v_mov_b32_e32 v18, v145
	v_mov_b32_e32 v19, v145
	v_mov_b32_e32 v20, v145
	v_mov_b32_e32 v21, v145
	v_mov_b32_e32 v22, v145
	v_mov_b32_e32 v23, v145
	v_mov_b32_e32 v24, v145
	v_mov_b32_e32 v25, v145
	v_mov_b32_e32 v26, v145
	v_mov_b32_e32 v27, v145
	v_mov_b32_e32 v28, v145
	v_mov_b32_e32 v29, v145
	v_mov_b32_e32 v30, v145
	v_mov_b32_e32 v31, v145
	v_mov_b32_e32 v32, 0
	v_mov_b32_e32 v33, v145
	v_mov_b32_e32 v34, v145
	v_mov_b32_e32 v35, v145
	v_mov_b32_e32 v36, v145
	v_mov_b32_e32 v37, v145
	v_mov_b32_e32 v38, v145
	v_mov_b32_e32 v39, v145
	v_mov_b32_e32 v40, v145
	v_mov_b32_e32 v41, v145
	v_mov_b32_e32 v42, v145
	v_mov_b32_e32 v43, v145
	v_mov_b32_e32 v44, v145
	v_mov_b32_e32 v45, v145
	v_mov_b32_e32 v46, v145
	v_mov_b32_e32 v47, v145
	v_mov_b32_e32 v48, 0
	v_mov_b32_e32 v49, v145
	v_mov_b32_e32 v50, v145
	v_mov_b32_e32 v51, v145
	v_mov_b32_e32 v52, v145
	v_mov_b32_e32 v53, v145
	v_mov_b32_e32 v54, v145
	v_mov_b32_e32 v55, v145
	v_mov_b32_e32 v56, v145
	v_mov_b32_e32 v57, v145
	v_mov_b32_e32 v58, v145
	v_mov_b32_e32 v59, v145
	v_mov_b32_e32 v60, v145
	v_mov_b32_e32 v61, v145
	v_mov_b32_e32 v62, v145
	v_mov_b32_e32 v63, v145
	v_mov_b32_e32 v64, 0
	v_mov_b32_e32 v65, v145
	v_mov_b32_e32 v66, v145
	v_mov_b32_e32 v67, v145
	v_mov_b32_e32 v68, v145
	v_mov_b32_e32 v69, v145
	v_mov_b32_e32 v70, v145
	v_mov_b32_e32 v71, v145
	v_mov_b32_e32 v72, v145
	v_mov_b32_e32 v73, v145
	v_mov_b32_e32 v74, v145
	v_mov_b32_e32 v75, v145
	v_mov_b32_e32 v76, v145
	v_mov_b32_e32 v77, v145
	v_mov_b32_e32 v78, v145
	v_mov_b32_e32 v79, v145
	v_mov_b32_e32 v80, 0
	v_mov_b32_e32 v81, v145
	v_mov_b32_e32 v82, v145
	v_mov_b32_e32 v83, v145
	v_mov_b32_e32 v84, v145
	v_mov_b32_e32 v85, v145
	v_mov_b32_e32 v86, v145
	v_mov_b32_e32 v87, v145
	v_mov_b32_e32 v88, v145
	v_mov_b32_e32 v89, v145
	v_mov_b32_e32 v90, v145
	v_mov_b32_e32 v91, v145
	v_mov_b32_e32 v92, v145
	v_mov_b32_e32 v93, v145
	v_mov_b32_e32 v94, v145
	v_mov_b32_e32 v95, v145
	v_mov_b32_e32 v96, 0
	v_mov_b32_e32 v97, v145
	v_mov_b32_e32 v98, v145
	v_mov_b32_e32 v99, v145
	v_mov_b32_e32 v100, v145
	v_mov_b32_e32 v101, v145
	v_mov_b32_e32 v102, v145
	v_mov_b32_e32 v103, v145
	v_mov_b32_e32 v104, v145
	v_mov_b32_e32 v105, v145
	v_mov_b32_e32 v106, v145
	v_mov_b32_e32 v107, v145
	v_mov_b32_e32 v108, v145
	v_mov_b32_e32 v109, v145
	v_mov_b32_e32 v110, v145
	v_mov_b32_e32 v111, v145
	v_mov_b32_e32 v112, 0
	v_mov_b32_e32 v113, v145
	v_mov_b32_e32 v114, v145
	v_mov_b32_e32 v115, v145
	v_mov_b32_e32 v116, v145
	v_mov_b32_e32 v117, v145
	v_mov_b32_e32 v118, v145
	v_mov_b32_e32 v119, v145
	v_mov_b32_e32 v120, v145
	v_mov_b32_e32 v121, v145
	v_mov_b32_e32 v122, v145
	v_mov_b32_e32 v123, v145
	v_mov_b32_e32 v124, v145
	v_mov_b32_e32 v125, v145
	v_mov_b32_e32 v126, v145
	v_mov_b32_e32 v127, v145
	s_waitcnt lgkmcnt(0)
	s_barrier
	v_readfirstlane_b32 s48, v188
	s_sub_u32 s48, s48, 16
	s_mov_b32 s49, 0
	s_mov_b32 s50, 0x8000
	s_mov_b32 s52, 0x10000
	v_and_b32_e32 v140, 63, v186
	v_and_b32_e32 v141, 15, v140
	v_lshrrev_b32_e32 v136, 4, v140
	v_bfe_u32 v137, v140, 1, 3
	v_xor_b32_e32 v132, v136, v137
	v_or_b32_e32 v136, 4, v136
	v_xor_b32_e32 v133, v136, v137
	v_lshlrev_b32_e32 v132, 4, v132
	v_lshlrev_b32_e32 v133, 4, v133
	v_lshl_add_u32 v132, v141, 7, v132
	v_lshl_add_u32 v133, v141, 7, v133
	v_bfe_u32 v136, v186, 6, 2
	v_lshl_add_u32 v134, v136, 13, v132
	v_lshl_add_u32 v135, v136, 13, v133
	v_lshrrev_b32_e32 v136, 8, v186
	v_lshl_add_u32 v132, v136, 14, v132
	v_lshl_add_u32 v133, v136, 14, v133
	v_readfirstlane_b32 s56, v128
	v_readfirstlane_b32 s57, v129
	s_and_b32 s53, s48, 0x400
	s_lshr_b32 s53, s53, 4
	s_sub_u32 s56, s56, s53
	s_subb_u32 s57, s57, 0
	v_subrev_u32_e32 v138, s56, v128
	s_add_u32 s62, s56, s28
	s_addc_u32 s63, s57, s29
	s_add_u32 s60, s56, s26
	s_addc_u32 s61, s57, s27
	s_add_u32 s58, s56, s24
	s_addc_u32 s59, s57, s25
	s_add_u32 s56, s56, s22
	s_addc_u32 s57, s57, s23
	v_readfirstlane_b32 s64, v130
	v_readfirstlane_b32 s65, v131
	s_and_b32 s53, s48, 0x400
	s_lshr_b32 s53, s53, 4
	s_sub_u32 s64, s64, s53
	s_subb_u32 s65, s65, 0
	v_subrev_u32_e32 v139, s64, v130
	s_add_u32 s70, s64, s28
	s_addc_u32 s71, s65, s29
	s_add_u32 s68, s64, s26
	s_addc_u32 s69, s65, s27
	s_add_u32 s66, s64, s24
	s_addc_u32 s67, s65, s25
	s_add_u32 s64, s64, s22
	s_addc_u32 s65, s65, s23
	s_add_u32 m0, s52, s48
	s_nop 0
	global_load_lds_dwordx4 v138, s[56:57]
	s_add_u32 s56, s56, 0x80
	s_addc_u32 s57, s57, 0
	s_add_u32 s53, s52, s48
	s_add_u32 m0, s53, 0x2000
	s_nop 0
	global_load_lds_dwordx4 v138, s[58:59]
	s_add_u32 s58, s58, 0x80
	s_addc_u32 s59, s59, 0
	s_add_u32 s53, s52, s48
	s_add_u32 m0, s53, 0x4000
	s_nop 0
	global_load_lds_dwordx4 v138, s[60:61]
	s_add_u32 s60, s60, 0x80
	s_addc_u32 s61, s61, 0
	s_add_u32 s53, s52, s48
	s_add_u32 m0, s53, 0x6000
	s_nop 0
	global_load_lds_dwordx4 v138, s[62:63]
	s_add_u32 s62, s62, 0x80
	s_addc_u32 s63, s63, 0
	s_add_u32 s51, s50, 0x10000
	s_sub_u32 s53, s51, 0x28000
	s_cmp_ge_u32 s51, 0x28000
	s_cselect_b32 s51, s53, s51
	s_add_u32 m0, s51, s48
	s_nop 0
	global_load_lds_dwordx4 v139, s[64:65]
	s_add_u32 s64, s64, 0x80
	s_addc_u32 s65, s65, 0
	s_add_u32 s53, s51, s48
	s_add_u32 m0, s53, 0x2000
	s_nop 0
	global_load_lds_dwordx4 v139, s[66:67]
	s_add_u32 s66, s66, 0x80
	s_addc_u32 s67, s67, 0
	s_add_u32 s53, s51, s48
	s_add_u32 m0, s53, 0x4000
	s_nop 0
	global_load_lds_dwordx4 v139, s[68:69]
	s_add_u32 s68, s68, 0x80
	s_addc_u32 s69, s69, 0
	s_add_u32 s53, s51, s48
	s_add_u32 m0, s53, 0x6000
	s_nop 0
	global_load_lds_dwordx4 v139, s[70:71]
	s_add_u32 s70, s70, 0x80
	s_addc_u32 s71, s71, 0
	v_add_u32_e32 v137, s50, v134
	v_add_u32_e32 v136, s49, v132
	ds_read_b128 v[164:167], v137
	ds_read_b128 v[168:171], v137 offset:2048
	ds_read_b128 v[172:175], v137 offset:4096
	ds_read_b128 v[176:179], v137 offset:6144
	ds_read_b128 v[224:227], v136
	ds_read_b128 v[228:231], v136 offset:2048
	ds_read_b128 v[232:235], v136 offset:4096
	ds_read_b128 v[236:239], v136 offset:6144
	.p2align 6
.Lg161_loop:
	s_add_u32 s51, s50, 0x10000
	s_sub_u32 s53, s51, 0x28000
	s_cmp_ge_u32 s51, 0x28000
	s_cselect_b32 s51, s53, s51
	s_add_u32 s52, s49, 0x20000
	s_sub_u32 s53, s52, 0x28000
	s_cmp_ge_u32 s52, 0x28000
	s_cselect_b32 s52, s53, s52
	v_add_u32_e32 v137, s50, v135
	s_waitcnt lgkmcnt(4)
	s_waitcnt lgkmcnt(3)
	v_mfma_f32_16x16x32_bf16 v[112:115], v[164:167], v[224:227], v[112:115]
	v_mfma_f32_16x16x32_bf16 v[120:123], v[168:171], v[224:227], v[120:123]
	v_mfma_f32_16x16x32_bf16 v[96:99], v[172:175], v[224:227], v[96:99]
	v_mfma_f32_16x16x32_bf16 v[104:107], v[176:179], v[224:227], v[104:107]
	s_add_u32 m0, s52, s48
	s_nop 0
	global_load_lds_dwordx4 v138, s[56:57]
	s_add_u32 s56, s56, 0x80
	s_addc_u32 s57, s57, 0
	s_add_u32 s53, s52, s48
	s_add_u32 m0, s53, 0x2000
	s_nop 0
	global_load_lds_dwordx4 v138, s[58:59]
	s_add_u32 s58, s58, 0x80
	s_addc_u32 s59, s59, 0
	ds_read_b128 v[224:227], v136 offset:8192
	ds_read_b128 v[180:183], v137
	s_waitcnt lgkmcnt(4)
	v_mfma_f32_16x16x32_bf16 v[116:119], v[164:167], v[228:231], v[116:119]
	v_mfma_f32_16x16x32_bf16 v[124:127], v[168:171], v[228:231], v[124:127]
	v_mfma_f32_16x16x32_bf16 v[100:103], v[172:175], v[228:231], v[100:103]
	v_mfma_f32_16x16x32_bf16 v[108:111], v[176:179], v[228:231], v[108:111]
	s_add_u32 s53, s52, s48
	s_add_u32 m0, s53, 0x4000
	s_nop 0
	global_load_lds_dwordx4 v138, s[60:61]
	s_add_u32 s60, s60, 0x80
	s_addc_u32 s61, s61, 0
	s_add_u32 s53, s52, s48
	s_add_u32 m0, s53, 0x6000
	s_nop 0
	global_load_lds_dwordx4 v138, s[62:63]
	s_add_u32 s62, s62, 0x80
	s_addc_u32 s63, s63, 0
	ds_read_b128 v[228:231], v136 offset:10240
	ds_read_b128 v[212:215], v137 offset:2048
	s_waitcnt lgkmcnt(5)
	v_mfma_f32_16x16x32_bf16 v[80:83], v[164:167], v[232:235], v[80:83]
	v_mfma_f32_16x16x32_bf16 v[88:91], v[168:171], v[232:235], v[88:91]
	v_mfma_f32_16x16x32_bf16 v[64:67], v[172:175], v[232:235], v[64:67]
	v_mfma_f32_16x16x32_bf16 v[72:75], v[176:179], v[232:235], v[72:75]
	ds_read_b128 v[232:235], v136 offset:12288
	ds_read_b128 v[216:219], v137 offset:4096
	s_waitcnt lgkmcnt(6)
	v_mfma_f32_16x16x32_bf16 v[84:87], v[164:167], v[236:239], v[84:87]
	v_mfma_f32_16x16x32_bf16 v[92:95], v[168:171], v[236:239], v[92:95]
	v_mfma_f32_16x16x32_bf16 v[68:71], v[172:175], v[236:239], v[68:71]
	v_mfma_f32_16x16x32_bf16 v[76:79], v[176:179], v[236:239], v[76:79]
	ds_read_b128 v[236:239], v136 offset:14336
	ds_read_b128 v[220:223], v137 offset:6144
	v_add_u32_e32 v136, s49, v133
	s_waitcnt lgkmcnt(7)
	v_mfma_f32_16x16x32_bf16 v[48:51], v[164:167], v[224:227], v[48:51]
	v_mfma_f32_16x16x32_bf16 v[56:59], v[168:171], v[224:227], v[56:59]
	v_mfma_f32_16x16x32_bf16 v[32:35], v[172:175], v[224:227], v[32:35]
	v_mfma_f32_16x16x32_bf16 v[40:43], v[176:179], v[224:227], v[40:43]
	ds_read_b128 v[224:227], v136
	s_waitcnt lgkmcnt(6)
	v_mfma_f32_16x16x32_bf16 v[52:55], v[164:167], v[228:231], v[52:55]
	v_mfma_f32_16x16x32_bf16 v[60:63], v[168:171], v[228:231], v[60:63]
	v_mfma_f32_16x16x32_bf16 v[36:39], v[172:175], v[228:231], v[36:39]
	v_mfma_f32_16x16x32_bf16 v[44:47], v[176:179], v[228:231], v[44:47]
	ds_read_b128 v[228:231], v136 offset:2048
	s_waitcnt lgkmcnt(5)
	v_mfma_f32_16x16x32_bf16 v[16:19], v[164:167], v[232:235], v[16:19]
	v_mfma_f32_16x16x32_bf16 v[24:27], v[168:171], v[232:235], v[24:27]
	v_mfma_f32_16x16x32_bf16 v[0:3], v[172:175], v[232:235], v[0:3]
	v_mfma_f32_16x16x32_bf16 v[8:11], v[176:179], v[232:235], v[8:11]
	ds_read_b128 v[232:235], v136 offset:4096
	s_waitcnt lgkmcnt(4)
	v_mfma_f32_16x16x32_bf16 v[20:23], v[164:167], v[236:239], v[20:23]
	v_mfma_f32_16x16x32_bf16 v[28:31], v[168:171], v[236:239], v[28:31]
	v_mfma_f32_16x16x32_bf16 v[4:7], v[172:175], v[236:239], v[4:7]
	v_mfma_f32_16x16x32_bf16 v[12:15], v[176:179], v[236:239], v[12:15]
	ds_read_b128 v[236:239], v136 offset:6144
	s_waitcnt lgkmcnt(4)
	s_waitcnt lgkmcnt(3)
	v_mfma_f32_16x16x32_bf16 v[112:115], v[180:183], v[224:227], v[112:115]
	v_mfma_f32_16x16x32_bf16 v[120:123], v[212:215], v[224:227], v[120:123]
	v_mfma_f32_16x16x32_bf16 v[96:99], v[216:219], v[224:227], v[96:99]
	v_mfma_f32_16x16x32_bf16 v[104:107], v[220:223], v[224:227], v[104:107]
	ds_read_b128 v[224:227], v136 offset:8192
	s_waitcnt lgkmcnt(3)
	v_mfma_f32_16x16x32_bf16 v[116:119], v[180:183], v[228:231], v[116:119]
	v_mfma_f32_16x16x32_bf16 v[124:127], v[212:215], v[228:231], v[124:127]
	v_mfma_f32_16x16x32_bf16 v[100:103], v[216:219], v[228:231], v[100:103]
	v_mfma_f32_16x16x32_bf16 v[108:111], v[220:223], v[228:231], v[108:111]
	ds_read_b128 v[228:231], v136 offset:10240
	s_waitcnt lgkmcnt(3)
	v_mfma_f32_16x16x32_bf16 v[80:83], v[180:183], v[232:235], v[80:83]
	v_mfma_f32_16x16x32_bf16 v[88:91], v[212:215], v[232:235], v[88:91]
	v_mfma_f32_16x16x32_bf16 v[64:67], v[216:219], v[232:235], v[64:67]
	v_mfma_f32_16x16x32_bf16 v[72:75], v[220:223], v[232:235], v[72:75]
	ds_read_b128 v[232:235], v136 offset:12288
	s_waitcnt lgkmcnt(3)
	v_mfma_f32_16x16x32_bf16 v[84:87], v[180:183], v[236:239], v[84:87]
	v_mfma_f32_16x16x32_bf16 v[92:95], v[212:215], v[236:239], v[92:95]
	v_mfma_f32_16x16x32_bf16 v[68:71], v[216:219], v[236:239], v[68:71]
	v_mfma_f32_16x16x32_bf16 v[76:79], v[220:223], v[236:239], v[76:79]
	ds_read_b128 v[236:239], v136 offset:14336
	s_waitcnt lgkmcnt(3)
	v_mfma_f32_16x16x32_bf16 v[48:51], v[180:183], v[224:227], v[48:51]
	v_mfma_f32_16x16x32_bf16 v[56:59], v[212:215], v[224:227], v[56:59]
	v_mfma_f32_16x16x32_bf16 v[32:35], v[216:219], v[224:227], v[32:35]
	v_mfma_f32_16x16x32_bf16 v[40:43], v[220:223], v[224:227], v[40:43]
	s_waitcnt lgkmcnt(2)
	v_mfma_f32_16x16x32_bf16 v[52:55], v[180:183], v[228:231], v[52:55]
	v_mfma_f32_16x16x32_bf16 v[60:63], v[212:215], v[228:231], v[60:63]
	v_mfma_f32_16x16x32_bf16 v[36:39], v[216:219], v[228:231], v[36:39]
	v_mfma_f32_16x16x32_bf16 v[44:47], v[220:223], v[228:231], v[44:47]
	s_waitcnt lgkmcnt(1)
	v_mfma_f32_16x16x32_bf16 v[16:19], v[180:183], v[232:235], v[16:19]
	v_mfma_f32_16x16x32_bf16 v[24:27], v[212:215], v[232:235], v[24:27]
	v_mfma_f32_16x16x32_bf16 v[0:3], v[216:219], v[232:235], v[0:3]
	v_mfma_f32_16x16x32_bf16 v[8:11], v[220:223], v[232:235], v[8:11]
	s_waitcnt lgkmcnt(0)
	s_add_u32 s4, s4, 0x80
	s_addc_u32 s5, s5, 0
	s_add_u32 s49, s49, 0x10000
	s_sub_u32 s53, s49, 0x28000
	s_cmp_ge_u32 s49, 0x28000
	s_cselect_b32 s49, s53, s49
	s_mov_b32 s50, s51
	s_waitcnt vmcnt(4)
	s_barrier
	v_add_u32_e32 v137, s50, v134
	v_add_u32_e32 v136, s49, v132
	ds_read_b128 v[164:167], v137
	ds_read_b128 v[168:171], v137 offset:2048
	ds_read_b128 v[172:175], v137 offset:4096
	ds_read_b128 v[176:179], v137 offset:6144
	ds_read_b128 v[224:227], v136
	ds_read_b128 v[228:231], v136 offset:2048
	ds_read_b128 v[232:235], v136 offset:4096
	s_add_u32 s51, s50, 0x10000
	s_sub_u32 s53, s51, 0x28000
	s_cmp_ge_u32 s51, 0x28000
	s_cselect_b32 s51, s53, s51
	s_add_u32 m0, s51, s48
	s_nop 0
	global_load_lds_dwordx4 v139, s[64:65]
	s_add_u32 s64, s64, 0x80
	s_addc_u32 s65, s65, 0
	s_add_u32 s53, s51, s48
	s_add_u32 m0, s53, 0x2000
	s_nop 0
	global_load_lds_dwordx4 v139, s[66:67]
	s_add_u32 s66, s66, 0x80
	s_addc_u32 s67, s67, 0
	s_add_u32 s53, s51, s48
	s_add_u32 m0, s53, 0x4000
	s_nop 0
	global_load_lds_dwordx4 v139, s[68:69]
	s_add_u32 s68, s68, 0x80
	s_addc_u32 s69, s69, 0
	s_add_u32 s53, s51, s48
	s_add_u32 m0, s53, 0x6000
	s_nop 0
	global_load_lds_dwordx4 v139, s[70:71]
	s_add_u32 s70, s70, 0x80
	s_addc_u32 s71, s71, 0
	v_mfma_f32_16x16x32_bf16 v[20:23], v[180:183], v[236:239], v[20:23]
	v_mfma_f32_16x16x32_bf16 v[28:31], v[212:215], v[236:239], v[28:31]
	v_mfma_f32_16x16x32_bf16 v[4:7], v[216:219], v[236:239], v[4:7]
	v_mfma_f32_16x16x32_bf16 v[12:15], v[220:223], v[236:239], v[12:15]
	ds_read_b128 v[236:239], v136 offset:6144
	s_cmpk_lg_i32 s4, 0xf00
	s_cbranch_scc1 .Lg161_loop
	s_add_u32 s51, s50, 0x10000
	s_sub_u32 s53, s51, 0x28000
	s_cmp_ge_u32 s51, 0x28000
	s_cselect_b32 s51, s53, s51
	v_add_u32_e32 v137, s50, v135
	s_waitcnt lgkmcnt(4)
	s_waitcnt lgkmcnt(3)
	v_mfma_f32_16x16x32_bf16 v[112:115], v[164:167], v[224:227], v[112:115]
	v_mfma_f32_16x16x32_bf16 v[120:123], v[168:171], v[224:227], v[120:123]
	v_mfma_f32_16x16x32_bf16 v[96:99], v[172:175], v[224:227], v[96:99]
	v_mfma_f32_16x16x32_bf16 v[104:107], v[176:179], v[224:227], v[104:107]
	ds_read_b128 v[224:227], v136 offset:8192
	ds_read_b128 v[180:183], v137
	s_waitcnt lgkmcnt(4)
	v_mfma_f32_16x16x32_bf16 v[116:119], v[164:167], v[228:231], v[116:119]
	v_mfma_f32_16x16x32_bf16 v[124:127], v[168:171], v[228:231], v[124:127]
	v_mfma_f32_16x16x32_bf16 v[100:103], v[172:175], v[228:231], v[100:103]
	v_mfma_f32_16x16x32_bf16 v[108:111], v[176:179], v[228:231], v[108:111]
	ds_read_b128 v[228:231], v136 offset:10240
	ds_read_b128 v[212:215], v137 offset:2048
	s_waitcnt lgkmcnt(5)
	v_mfma_f32_16x16x32_bf16 v[80:83], v[164:167], v[232:235], v[80:83]
	v_mfma_f32_16x16x32_bf16 v[88:91], v[168:171], v[232:235], v[88:91]
	v_mfma_f32_16x16x32_bf16 v[64:67], v[172:175], v[232:235], v[64:67]
	v_mfma_f32_16x16x32_bf16 v[72:75], v[176:179], v[232:235], v[72:75]
	ds_read_b128 v[232:235], v136 offset:12288
	ds_read_b128 v[216:219], v137 offset:4096
	s_waitcnt lgkmcnt(6)
	v_mfma_f32_16x16x32_bf16 v[84:87], v[164:167], v[236:239], v[84:87]
	v_mfma_f32_16x16x32_bf16 v[92:95], v[168:171], v[236:239], v[92:95]
	v_mfma_f32_16x16x32_bf16 v[68:71], v[172:175], v[236:239], v[68:71]
	v_mfma_f32_16x16x32_bf16 v[76:79], v[176:179], v[236:239], v[76:79]
	ds_read_b128 v[236:239], v136 offset:14336
	ds_read_b128 v[220:223], v137 offset:6144
	v_add_u32_e32 v136, s49, v133
	s_waitcnt lgkmcnt(7)
	v_mfma_f32_16x16x32_bf16 v[48:51], v[164:167], v[224:227], v[48:51]
	v_mfma_f32_16x16x32_bf16 v[56:59], v[168:171], v[224:227], v[56:59]
	v_mfma_f32_16x16x32_bf16 v[32:35], v[172:175], v[224:227], v[32:35]
	v_mfma_f32_16x16x32_bf16 v[40:43], v[176:179], v[224:227], v[40:43]
	ds_read_b128 v[224:227], v136
	s_waitcnt lgkmcnt(6)
	v_mfma_f32_16x16x32_bf16 v[52:55], v[164:167], v[228:231], v[52:55]
	v_mfma_f32_16x16x32_bf16 v[60:63], v[168:171], v[228:231], v[60:63]
	v_mfma_f32_16x16x32_bf16 v[36:39], v[172:175], v[228:231], v[36:39]
	v_mfma_f32_16x16x32_bf16 v[44:47], v[176:179], v[228:231], v[44:47]
	ds_read_b128 v[228:231], v136 offset:2048
	s_waitcnt lgkmcnt(5)
	v_mfma_f32_16x16x32_bf16 v[16:19], v[164:167], v[232:235], v[16:19]
	v_mfma_f32_16x16x32_bf16 v[24:27], v[168:171], v[232:235], v[24:27]
	v_mfma_f32_16x16x32_bf16 v[0:3], v[172:175], v[232:235], v[0:3]
	v_mfma_f32_16x16x32_bf16 v[8:11], v[176:179], v[232:235], v[8:11]
	ds_read_b128 v[232:235], v136 offset:4096
	s_waitcnt lgkmcnt(4)
	v_mfma_f32_16x16x32_bf16 v[20:23], v[164:167], v[236:239], v[20:23]
	v_mfma_f32_16x16x32_bf16 v[28:31], v[168:171], v[236:239], v[28:31]
	v_mfma_f32_16x16x32_bf16 v[4:7], v[172:175], v[236:239], v[4:7]
	v_mfma_f32_16x16x32_bf16 v[12:15], v[176:179], v[236:239], v[12:15]
	ds_read_b128 v[236:239], v136 offset:6144
	s_waitcnt lgkmcnt(4)
	s_waitcnt lgkmcnt(3)
	v_mfma_f32_16x16x32_bf16 v[112:115], v[180:183], v[224:227], v[112:115]
	v_mfma_f32_16x16x32_bf16 v[120:123], v[212:215], v[224:227], v[120:123]
	v_mfma_f32_16x16x32_bf16 v[96:99], v[216:219], v[224:227], v[96:99]
	v_mfma_f32_16x16x32_bf16 v[104:107], v[220:223], v[224:227], v[104:107]
	ds_read_b128 v[224:227], v136 offset:8192
	s_waitcnt lgkmcnt(3)
	v_mfma_f32_16x16x32_bf16 v[116:119], v[180:183], v[228:231], v[116:119]
	v_mfma_f32_16x16x32_bf16 v[124:127], v[212:215], v[228:231], v[124:127]
	v_mfma_f32_16x16x32_bf16 v[100:103], v[216:219], v[228:231], v[100:103]
	v_mfma_f32_16x16x32_bf16 v[108:111], v[220:223], v[228:231], v[108:111]
	ds_read_b128 v[228:231], v136 offset:10240
	s_waitcnt lgkmcnt(3)
	v_mfma_f32_16x16x32_bf16 v[80:83], v[180:183], v[232:235], v[80:83]
	v_mfma_f32_16x16x32_bf16 v[88:91], v[212:215], v[232:235], v[88:91]
	v_mfma_f32_16x16x32_bf16 v[64:67], v[216:219], v[232:235], v[64:67]
	v_mfma_f32_16x16x32_bf16 v[72:75], v[220:223], v[232:235], v[72:75]
	ds_read_b128 v[232:235], v136 offset:12288
	s_waitcnt lgkmcnt(3)
	v_mfma_f32_16x16x32_bf16 v[84:87], v[180:183], v[236:239], v[84:87]
	v_mfma_f32_16x16x32_bf16 v[92:95], v[212:215], v[236:239], v[92:95]
	v_mfma_f32_16x16x32_bf16 v[68:71], v[216:219], v[236:239], v[68:71]
	v_mfma_f32_16x16x32_bf16 v[76:79], v[220:223], v[236:239], v[76:79]
	ds_read_b128 v[236:239], v136 offset:14336
	s_waitcnt lgkmcnt(3)
	v_mfma_f32_16x16x32_bf16 v[48:51], v[180:183], v[224:227], v[48:51]
	v_mfma_f32_16x16x32_bf16 v[56:59], v[212:215], v[224:227], v[56:59]
	v_mfma_f32_16x16x32_bf16 v[32:35], v[216:219], v[224:227], v[32:35]
	v_mfma_f32_16x16x32_bf16 v[40:43], v[220:223], v[224:227], v[40:43]
	s_waitcnt lgkmcnt(2)
	v_mfma_f32_16x16x32_bf16 v[52:55], v[180:183], v[228:231], v[52:55]
	v_mfma_f32_16x16x32_bf16 v[60:63], v[212:215], v[228:231], v[60:63]
	v_mfma_f32_16x16x32_bf16 v[36:39], v[216:219], v[228:231], v[36:39]
	v_mfma_f32_16x16x32_bf16 v[44:47], v[220:223], v[228:231], v[44:47]
	s_waitcnt lgkmcnt(1)
	v_mfma_f32_16x16x32_bf16 v[16:19], v[180:183], v[232:235], v[16:19]
	v_mfma_f32_16x16x32_bf16 v[24:27], v[212:215], v[232:235], v[24:27]
	v_mfma_f32_16x16x32_bf16 v[0:3], v[216:219], v[232:235], v[0:3]
	v_mfma_f32_16x16x32_bf16 v[8:11], v[220:223], v[232:235], v[8:11]
	s_waitcnt lgkmcnt(0)
	s_add_u32 s4, s4, 0x80
	s_addc_u32 s5, s5, 0
	s_add_u32 s49, s49, 0x10000
	s_sub_u32 s53, s49, 0x28000
	s_cmp_ge_u32 s49, 0x28000
	s_cselect_b32 s49, s53, s49
	s_mov_b32 s50, s51
	s_waitcnt vmcnt(0)
	s_barrier
	v_add_u32_e32 v137, s50, v134
	v_add_u32_e32 v136, s49, v132
	ds_read_b128 v[164:167], v137
	ds_read_b128 v[168:171], v137 offset:2048
	ds_read_b128 v[172:175], v137 offset:4096
	ds_read_b128 v[176:179], v137 offset:6144
	ds_read_b128 v[224:227], v136
	ds_read_b128 v[228:231], v136 offset:2048
	ds_read_b128 v[232:235], v136 offset:4096
	v_mfma_f32_16x16x32_bf16 v[20:23], v[180:183], v[236:239], v[20:23]
	v_mfma_f32_16x16x32_bf16 v[28:31], v[212:215], v[236:239], v[28:31]
	v_mfma_f32_16x16x32_bf16 v[4:7], v[216:219], v[236:239], v[4:7]
	v_mfma_f32_16x16x32_bf16 v[12:15], v[220:223], v[236:239], v[12:15]
	ds_read_b128 v[236:239], v136 offset:6144
	v_add_u32_e32 v137, s50, v135
	s_waitcnt lgkmcnt(4)
	s_waitcnt lgkmcnt(3)
	v_mfma_f32_16x16x32_bf16 v[112:115], v[164:167], v[224:227], v[112:115]
	v_mfma_f32_16x16x32_bf16 v[120:123], v[168:171], v[224:227], v[120:123]
	v_mfma_f32_16x16x32_bf16 v[96:99], v[172:175], v[224:227], v[96:99]
	v_mfma_f32_16x16x32_bf16 v[104:107], v[176:179], v[224:227], v[104:107]
	ds_read_b128 v[224:227], v136 offset:8192
	ds_read_b128 v[180:183], v137
	s_waitcnt lgkmcnt(4)
	v_mfma_f32_16x16x32_bf16 v[116:119], v[164:167], v[228:231], v[116:119]
	v_mfma_f32_16x16x32_bf16 v[124:127], v[168:171], v[228:231], v[124:127]
	v_mfma_f32_16x16x32_bf16 v[100:103], v[172:175], v[228:231], v[100:103]
	v_mfma_f32_16x16x32_bf16 v[108:111], v[176:179], v[228:231], v[108:111]
	ds_read_b128 v[228:231], v136 offset:10240
	ds_read_b128 v[212:215], v137 offset:2048
	s_waitcnt lgkmcnt(5)
	v_mfma_f32_16x16x32_bf16 v[80:83], v[164:167], v[232:235], v[80:83]
	v_mfma_f32_16x16x32_bf16 v[88:91], v[168:171], v[232:235], v[88:91]
	v_mfma_f32_16x16x32_bf16 v[64:67], v[172:175], v[232:235], v[64:67]
	v_mfma_f32_16x16x32_bf16 v[72:75], v[176:179], v[232:235], v[72:75]
	ds_read_b128 v[232:235], v136 offset:12288
	ds_read_b128 v[216:219], v137 offset:4096
	s_waitcnt lgkmcnt(6)
	v_mfma_f32_16x16x32_bf16 v[84:87], v[164:167], v[236:239], v[84:87]
	v_mfma_f32_16x16x32_bf16 v[92:95], v[168:171], v[236:239], v[92:95]
	v_mfma_f32_16x16x32_bf16 v[68:71], v[172:175], v[236:239], v[68:71]
	v_mfma_f32_16x16x32_bf16 v[76:79], v[176:179], v[236:239], v[76:79]
	ds_read_b128 v[236:239], v136 offset:14336
	ds_read_b128 v[220:223], v137 offset:6144
	v_add_u32_e32 v136, s49, v133
	s_waitcnt lgkmcnt(7)
	v_mfma_f32_16x16x32_bf16 v[48:51], v[164:167], v[224:227], v[48:51]
	v_mfma_f32_16x16x32_bf16 v[56:59], v[168:171], v[224:227], v[56:59]
	v_mfma_f32_16x16x32_bf16 v[32:35], v[172:175], v[224:227], v[32:35]
	v_mfma_f32_16x16x32_bf16 v[40:43], v[176:179], v[224:227], v[40:43]
	ds_read_b128 v[224:227], v136
	s_waitcnt lgkmcnt(6)
	v_mfma_f32_16x16x32_bf16 v[52:55], v[164:167], v[228:231], v[52:55]
	v_mfma_f32_16x16x32_bf16 v[60:63], v[168:171], v[228:231], v[60:63]
	v_mfma_f32_16x16x32_bf16 v[36:39], v[172:175], v[228:231], v[36:39]
	v_mfma_f32_16x16x32_bf16 v[44:47], v[176:179], v[228:231], v[44:47]
	ds_read_b128 v[228:231], v136 offset:2048
	s_waitcnt lgkmcnt(5)
	v_mfma_f32_16x16x32_bf16 v[16:19], v[164:167], v[232:235], v[16:19]
	v_mfma_f32_16x16x32_bf16 v[24:27], v[168:171], v[232:235], v[24:27]
	v_mfma_f32_16x16x32_bf16 v[0:3], v[172:175], v[232:235], v[0:3]
	v_mfma_f32_16x16x32_bf16 v[8:11], v[176:179], v[232:235], v[8:11]
	ds_read_b128 v[232:235], v136 offset:4096
	s_waitcnt lgkmcnt(4)
	v_mfma_f32_16x16x32_bf16 v[20:23], v[164:167], v[236:239], v[20:23]
	v_mfma_f32_16x16x32_bf16 v[28:31], v[168:171], v[236:239], v[28:31]
	v_mfma_f32_16x16x32_bf16 v[4:7], v[172:175], v[236:239], v[4:7]
	v_mfma_f32_16x16x32_bf16 v[12:15], v[176:179], v[236:239], v[12:15]
	ds_read_b128 v[236:239], v136 offset:6144
	s_waitcnt lgkmcnt(4)
	s_waitcnt lgkmcnt(3)
	v_mfma_f32_16x16x32_bf16 v[112:115], v[180:183], v[224:227], v[112:115]
	v_mfma_f32_16x16x32_bf16 v[120:123], v[212:215], v[224:227], v[120:123]
	v_mfma_f32_16x16x32_bf16 v[96:99], v[216:219], v[224:227], v[96:99]
	v_mfma_f32_16x16x32_bf16 v[104:107], v[220:223], v[224:227], v[104:107]
	ds_read_b128 v[224:227], v136 offset:8192
	s_waitcnt lgkmcnt(3)
	v_mfma_f32_16x16x32_bf16 v[116:119], v[180:183], v[228:231], v[116:119]
	v_mfma_f32_16x16x32_bf16 v[124:127], v[212:215], v[228:231], v[124:127]
	v_mfma_f32_16x16x32_bf16 v[100:103], v[216:219], v[228:231], v[100:103]
	v_mfma_f32_16x16x32_bf16 v[108:111], v[220:223], v[228:231], v[108:111]
	ds_read_b128 v[228:231], v136 offset:10240
	s_waitcnt lgkmcnt(3)
	v_mfma_f32_16x16x32_bf16 v[80:83], v[180:183], v[232:235], v[80:83]
	v_mfma_f32_16x16x32_bf16 v[88:91], v[212:215], v[232:235], v[88:91]
	v_mfma_f32_16x16x32_bf16 v[64:67], v[216:219], v[232:235], v[64:67]
	v_mfma_f32_16x16x32_bf16 v[72:75], v[220:223], v[232:235], v[72:75]
	ds_read_b128 v[232:235], v136 offset:12288
	s_waitcnt lgkmcnt(3)
	v_mfma_f32_16x16x32_bf16 v[84:87], v[180:183], v[236:239], v[84:87]
	v_mfma_f32_16x16x32_bf16 v[92:95], v[212:215], v[236:239], v[92:95]
	v_mfma_f32_16x16x32_bf16 v[68:71], v[216:219], v[236:239], v[68:71]
	v_mfma_f32_16x16x32_bf16 v[76:79], v[220:223], v[236:239], v[76:79]
	ds_read_b128 v[236:239], v136 offset:14336
	s_waitcnt lgkmcnt(3)
	v_mfma_f32_16x16x32_bf16 v[48:51], v[180:183], v[224:227], v[48:51]
	v_mfma_f32_16x16x32_bf16 v[56:59], v[212:215], v[224:227], v[56:59]
	v_mfma_f32_16x16x32_bf16 v[32:35], v[216:219], v[224:227], v[32:35]
	v_mfma_f32_16x16x32_bf16 v[40:43], v[220:223], v[224:227], v[40:43]
	s_waitcnt lgkmcnt(2)
	v_mfma_f32_16x16x32_bf16 v[52:55], v[180:183], v[228:231], v[52:55]
	v_mfma_f32_16x16x32_bf16 v[60:63], v[212:215], v[228:231], v[60:63]
	v_mfma_f32_16x16x32_bf16 v[36:39], v[216:219], v[228:231], v[36:39]
	v_mfma_f32_16x16x32_bf16 v[44:47], v[220:223], v[228:231], v[44:47]
	s_waitcnt lgkmcnt(1)
	v_mfma_f32_16x16x32_bf16 v[16:19], v[180:183], v[232:235], v[16:19]
	v_mfma_f32_16x16x32_bf16 v[24:27], v[212:215], v[232:235], v[24:27]
	v_mfma_f32_16x16x32_bf16 v[0:3], v[216:219], v[232:235], v[0:3]
	v_mfma_f32_16x16x32_bf16 v[8:11], v[220:223], v[232:235], v[8:11]
	s_waitcnt lgkmcnt(0)
	s_waitcnt vmcnt(0)
	s_barrier
	v_mfma_f32_16x16x32_bf16 v[20:23], v[180:183], v[236:239], v[20:23]
	v_mfma_f32_16x16x32_bf16 v[28:31], v[212:215], v[236:239], v[28:31]
	v_mfma_f32_16x16x32_bf16 v[4:7], v[216:219], v[236:239], v[4:7]
	v_mfma_f32_16x16x32_bf16 v[12:15], v[220:223], v[236:239], v[12:15]
	s_nop 15
	v_permlane16_swap_b32_e32 v112, v116
	v_permlane16_swap_b32_e32 v113, v117
	v_permlane16_swap_b32_e32 v114, v118
	v_permlane16_swap_b32_e32 v115, v119
	v_permlane16_swap_b32_e32 v120, v124
	v_permlane16_swap_b32_e32 v121, v125
	v_permlane16_swap_b32_e32 v122, v126
	v_permlane16_swap_b32_e32 v123, v127
	v_permlane16_swap_b32_e32 v96, v100
	v_permlane16_swap_b32_e32 v97, v101
	v_permlane16_swap_b32_e32 v98, v102
	v_permlane16_swap_b32_e32 v99, v103
	v_permlane16_swap_b32_e32 v104, v108
	v_permlane16_swap_b32_e32 v105, v109
	v_permlane16_swap_b32_e32 v106, v110
	v_permlane16_swap_b32_e32 v107, v111
	v_permlane16_swap_b32_e32 v80, v84
	v_permlane16_swap_b32_e32 v81, v85
	v_permlane16_swap_b32_e32 v82, v86
	v_permlane16_swap_b32_e32 v83, v87
	v_permlane16_swap_b32_e32 v88, v92
	v_permlane16_swap_b32_e32 v89, v93
	v_permlane16_swap_b32_e32 v90, v94
	v_permlane16_swap_b32_e32 v91, v95
	v_permlane16_swap_b32_e32 v64, v68
	v_permlane16_swap_b32_e32 v65, v69
	v_permlane16_swap_b32_e32 v66, v70
	v_permlane16_swap_b32_e32 v67, v71
	v_permlane16_swap_b32_e32 v72, v76
	v_permlane16_swap_b32_e32 v73, v77
	v_permlane16_swap_b32_e32 v74, v78
	v_permlane16_swap_b32_e32 v75, v79
	v_permlane16_swap_b32_e32 v48, v52
	v_permlane16_swap_b32_e32 v49, v53
	v_permlane16_swap_b32_e32 v50, v54
	v_permlane16_swap_b32_e32 v51, v55
	v_permlane16_swap_b32_e32 v56, v60
	v_permlane16_swap_b32_e32 v57, v61
	v_permlane16_swap_b32_e32 v58, v62
	v_permlane16_swap_b32_e32 v59, v63
	v_permlane16_swap_b32_e32 v32, v36
	v_permlane16_swap_b32_e32 v33, v37
	v_permlane16_swap_b32_e32 v34, v38
	v_permlane16_swap_b32_e32 v35, v39
	v_permlane16_swap_b32_e32 v40, v44
	v_permlane16_swap_b32_e32 v41, v45
	v_permlane16_swap_b32_e32 v42, v46
	v_permlane16_swap_b32_e32 v43, v47
	v_permlane16_swap_b32_e32 v16, v20
	v_permlane16_swap_b32_e32 v17, v21
	v_permlane16_swap_b32_e32 v18, v22
	v_permlane16_swap_b32_e32 v19, v23
	v_permlane16_swap_b32_e32 v24, v28
	v_permlane16_swap_b32_e32 v25, v29
	v_permlane16_swap_b32_e32 v26, v30
	v_permlane16_swap_b32_e32 v27, v31
	v_permlane16_swap_b32_e32 v0, v4
	v_permlane16_swap_b32_e32 v1, v5
	v_permlane16_swap_b32_e32 v2, v6
	v_permlane16_swap_b32_e32 v3, v7
	v_permlane16_swap_b32_e32 v8, v12
	v_permlane16_swap_b32_e32 v9, v13
	v_permlane16_swap_b32_e32 v10, v14
	v_permlane16_swap_b32_e32 v11, v15
	v_permlane32_swap_b32_e32 v112, v116
	v_permlane32_swap_b32_e32 v113, v117
	v_permlane32_swap_b32_e32 v114, v118
	v_permlane32_swap_b32_e32 v115, v119
	v_permlane32_swap_b32_e32 v120, v124
	v_permlane32_swap_b32_e32 v121, v125
	v_permlane32_swap_b32_e32 v122, v126
	v_permlane32_swap_b32_e32 v123, v127
	v_permlane32_swap_b32_e32 v96, v100
	v_permlane32_swap_b32_e32 v97, v101
	v_permlane32_swap_b32_e32 v98, v102
	v_permlane32_swap_b32_e32 v99, v103
	v_permlane32_swap_b32_e32 v104, v108
	v_permlane32_swap_b32_e32 v105, v109
	v_permlane32_swap_b32_e32 v106, v110
	v_permlane32_swap_b32_e32 v107, v111
	v_permlane32_swap_b32_e32 v80, v84
	v_permlane32_swap_b32_e32 v81, v85
	v_permlane32_swap_b32_e32 v82, v86
	v_permlane32_swap_b32_e32 v83, v87
	v_permlane32_swap_b32_e32 v88, v92
	v_permlane32_swap_b32_e32 v89, v93
	v_permlane32_swap_b32_e32 v90, v94
	v_permlane32_swap_b32_e32 v91, v95
	v_permlane32_swap_b32_e32 v64, v68
	v_permlane32_swap_b32_e32 v65, v69
	v_permlane32_swap_b32_e32 v66, v70
	v_permlane32_swap_b32_e32 v67, v71
	v_permlane32_swap_b32_e32 v72, v76
	v_permlane32_swap_b32_e32 v73, v77
	v_permlane32_swap_b32_e32 v74, v78
	v_permlane32_swap_b32_e32 v75, v79
	v_permlane32_swap_b32_e32 v48, v52
	v_permlane32_swap_b32_e32 v49, v53
	v_permlane32_swap_b32_e32 v50, v54
	v_permlane32_swap_b32_e32 v51, v55
	v_permlane32_swap_b32_e32 v56, v60
	v_permlane32_swap_b32_e32 v57, v61
	v_permlane32_swap_b32_e32 v58, v62
	v_permlane32_swap_b32_e32 v59, v63
	v_permlane32_swap_b32_e32 v32, v36
	v_permlane32_swap_b32_e32 v33, v37
	v_permlane32_swap_b32_e32 v34, v38
	v_permlane32_swap_b32_e32 v35, v39
	v_permlane32_swap_b32_e32 v40, v44
	v_permlane32_swap_b32_e32 v41, v45
	v_permlane32_swap_b32_e32 v42, v46
	v_permlane32_swap_b32_e32 v43, v47
	v_permlane32_swap_b32_e32 v16, v20
	v_permlane32_swap_b32_e32 v17, v21
	v_permlane32_swap_b32_e32 v18, v22
	v_permlane32_swap_b32_e32 v19, v23
	v_permlane32_swap_b32_e32 v24, v28
	v_permlane32_swap_b32_e32 v25, v29
	v_permlane32_swap_b32_e32 v26, v30
	v_permlane32_swap_b32_e32 v27, v31
	v_permlane32_swap_b32_e32 v0, v4
	v_permlane32_swap_b32_e32 v1, v5
	v_permlane32_swap_b32_e32 v2, v6
	v_permlane32_swap_b32_e32 v3, v7
	v_permlane32_swap_b32_e32 v8, v12
	v_permlane32_swap_b32_e32 v9, v13
	v_permlane32_swap_b32_e32 v10, v14
	v_permlane32_swap_b32_e32 v11, v15
	s_nop 1

.LBB0_164:
	s_ashr_i32 s33, s30, 2
	s_and_b32 s33, s33, -8
	s_or_b32 s33, s33, s3
	s_ashr_i32 s37, s33, 31
	s_lshr_b32 s37, s37, 29
	s_add_i32 s37, s33, s37
	s_ashr_i32 s39, s37, 3
	s_and_b32 s37, s37, 0x1ffff8
	s_sub_i32 s37, s33, s37
	s_lshl_b32 s38, s30, 8
	s_lshl_b32 s37, s37, 11
	s_and_b32 s38, s38, 0x700
	s_or_b32 s37, s37, s38
	s_lshl_b32 s38, s30, 5
	s_lshl_b32 s40, s39, 10
	s_and_b32 s38, s38, 0x300
	v_add_u32_e32 v0, s37, v149
	s_or_b32 s38, s40, s38
	v_ashrrev_i32_e32 v1, 31, v0
	v_add_u32_e32 v2, s38, v149
	v_lshlrev_b64 v[0:1], 12, v[0:1]
	v_ashrrev_i32_e32 v3, 31, v2
	v_readfirstlane_b32 s41, v150
	v_lshl_add_u64 v[0:1], v[130:131], 0, v[0:1]
	v_lshlrev_b64 v[2:3], 12, v[2:3]
	s_add_i32 m0, s41, -16
	v_readfirstlane_b32 s41, v128
	v_lshl_add_u64 v[2:3], v[132:133], 0, v[2:3]
	global_load_lds_dwordx4 v[0:1], off
	s_add_i32 m0, s41, -16
	v_readfirstlane_b32 s41, v160
	global_load_lds_dwordx4 v[2:3], off
	v_lshl_add_u64 v[4:5], v[0:1], 0, s[12:13]
	s_add_i32 m0, s41, -16
	v_readfirstlane_b32 s41, v161
	global_load_lds_dwordx4 v[4:5], off
	v_lshl_add_u64 v[4:5], v[2:3], 0, s[12:13]
	s_add_i32 m0, s41, -16
	v_readfirstlane_b32 s41, v162
	global_load_lds_dwordx4 v[4:5], off
	v_lshl_add_u64 v[4:5], v[0:1], 0, s[14:15]
	s_add_i32 m0, s41, -16
	v_readfirstlane_b32 s41, v163
	global_load_lds_dwordx4 v[4:5], off
	v_lshl_add_u64 v[4:5], v[2:3], 0, s[14:15]
	s_add_i32 m0, s41, -16
	v_readfirstlane_b32 s41, v164
	global_load_lds_dwordx4 v[4:5], off
	v_lshl_add_u64 v[0:1], v[0:1], 0, s[16:17]
	s_add_i32 m0, s41, -16
	v_readfirstlane_b32 s41, v165
	global_load_lds_dwordx4 v[0:1], off
	v_lshl_add_u64 v[0:1], v[2:3], 0, s[16:17]
	s_add_i32 m0, s41, -16
	s_and_b32 s28, s31, 0x700
	global_load_lds_dwordx4 v[0:1], off
	s_lshl_b32 s33, s33, 11
	s_or_b32 s28, s28, s33
	v_add_u32_e32 v0, s28, v149
	s_lshl_b32 s28, s39, 14
	v_subrev_u32_e32 v0, s28, v0
	s_and_b32 s29, s35, 0x300
	v_ashrrev_i32_e32 v1, 31, v0
	v_lshlrev_b64 v[0:1], 12, v[0:1]
	s_or_b32 s28, s29, s40
	v_lshl_add_u64 v[138:139], v[134:135], 0, v[0:1]
	v_add_u32_e32 v0, s28, v149
	v_ashrrev_i32_e32 v1, 31, v0
	v_lshlrev_b64 v[0:1], 12, v[0:1]
	v_lshl_add_u64 v[140:141], v[136:137], 0, v[0:1]
	s_mov_b32 s39, 0
	s_mov_b64 s[28:29], 0
	v_mov_b32_e32 v0, 0
	v_mov_b32_e32 v1, v129
	v_mov_b32_e32 v2, v129
	v_mov_b32_e32 v3, v129
	v_mov_b32_e32 v4, v129
	v_mov_b32_e32 v5, v129
	v_mov_b32_e32 v6, v129
	v_mov_b32_e32 v7, v129
	v_mov_b32_e32 v8, v129
	v_mov_b32_e32 v9, v129
	v_mov_b32_e32 v10, v129
	v_mov_b32_e32 v11, v129
	v_mov_b32_e32 v12, v129
	v_mov_b32_e32 v13, v129
	v_mov_b32_e32 v14, v129
	v_mov_b32_e32 v15, v129
	v_mov_b32_e32 v16, 0
	v_mov_b32_e32 v17, v129
	v_mov_b32_e32 v18, v129
	v_mov_b32_e32 v19, v129
	v_mov_b32_e32 v20, v129
	v_mov_b32_e32 v21, v129
	v_mov_b32_e32 v22, v129
	v_mov_b32_e32 v23, v129
	v_mov_b32_e32 v24, v129
	v_mov_b32_e32 v25, v129
	v_mov_b32_e32 v26, v129
	v_mov_b32_e32 v27, v129
	v_mov_b32_e32 v28, v129
	v_mov_b32_e32 v29, v129
	v_mov_b32_e32 v30, v129
	v_mov_b32_e32 v31, v129
	v_mov_b32_e32 v32, 0
	v_mov_b32_e32 v33, v129
	v_mov_b32_e32 v34, v129
	v_mov_b32_e32 v35, v129
	v_mov_b32_e32 v36, v129
	v_mov_b32_e32 v37, v129
	v_mov_b32_e32 v38, v129
	v_mov_b32_e32 v39, v129
	v_mov_b32_e32 v40, v129
	v_mov_b32_e32 v41, v129
	v_mov_b32_e32 v42, v129
	v_mov_b32_e32 v43, v129
	v_mov_b32_e32 v44, v129
	v_mov_b32_e32 v45, v129
	v_mov_b32_e32 v46, v129
	v_mov_b32_e32 v47, v129
	v_mov_b32_e32 v48, 0
	v_mov_b32_e32 v49, v129
	v_mov_b32_e32 v50, v129
	v_mov_b32_e32 v51, v129
	v_mov_b32_e32 v52, v129
	v_mov_b32_e32 v53, v129
	v_mov_b32_e32 v54, v129
	v_mov_b32_e32 v55, v129
	v_mov_b32_e32 v56, v129
	v_mov_b32_e32 v57, v129
	v_mov_b32_e32 v58, v129
	v_mov_b32_e32 v59, v129
	v_mov_b32_e32 v60, v129
	v_mov_b32_e32 v61, v129
	v_mov_b32_e32 v62, v129
	v_mov_b32_e32 v63, v129
	v_mov_b32_e32 v64, 0
	v_mov_b32_e32 v65, v129
	v_mov_b32_e32 v66, v129
	v_mov_b32_e32 v67, v129
	v_mov_b32_e32 v68, v129
	v_mov_b32_e32 v69, v129
	v_mov_b32_e32 v70, v129
	v_mov_b32_e32 v71, v129
	v_mov_b32_e32 v72, v129
	v_mov_b32_e32 v73, v129
	v_mov_b32_e32 v74, v129
	v_mov_b32_e32 v75, v129
	v_mov_b32_e32 v76, v129
	v_mov_b32_e32 v77, v129
	v_mov_b32_e32 v78, v129
	v_mov_b32_e32 v79, v129
	v_mov_b32_e32 v80, 0
	v_mov_b32_e32 v81, v129
	v_mov_b32_e32 v82, v129
	v_mov_b32_e32 v83, v129
	v_mov_b32_e32 v84, v129
	v_mov_b32_e32 v85, v129
	v_mov_b32_e32 v86, v129
	v_mov_b32_e32 v87, v129
	v_mov_b32_e32 v88, v129
	v_mov_b32_e32 v89, v129
	v_mov_b32_e32 v90, v129
	v_mov_b32_e32 v91, v129
	v_mov_b32_e32 v92, v129
	v_mov_b32_e32 v93, v129
	v_mov_b32_e32 v94, v129
	v_mov_b32_e32 v95, v129
	v_mov_b32_e32 v96, 0
	v_mov_b32_e32 v97, v129
	v_mov_b32_e32 v98, v129
	v_mov_b32_e32 v99, v129
	v_mov_b32_e32 v100, v129
	v_mov_b32_e32 v101, v129
	v_mov_b32_e32 v102, v129
	v_mov_b32_e32 v103, v129
	v_mov_b32_e32 v104, v129
	v_mov_b32_e32 v105, v129
	v_mov_b32_e32 v106, v129
	v_mov_b32_e32 v107, v129
	v_mov_b32_e32 v108, v129
	v_mov_b32_e32 v109, v129
	v_mov_b32_e32 v110, v129
	v_mov_b32_e32 v111, v129
	v_mov_b32_e32 v112, 0
	v_mov_b32_e32 v113, v129
	v_mov_b32_e32 v114, v129
	v_mov_b32_e32 v115, v129
	v_mov_b32_e32 v116, v129
	v_mov_b32_e32 v117, v129
	v_mov_b32_e32 v118, v129
	v_mov_b32_e32 v119, v129
	v_mov_b32_e32 v120, v129
	v_mov_b32_e32 v121, v129
	v_mov_b32_e32 v122, v129
	v_mov_b32_e32 v123, v129
	v_mov_b32_e32 v124, v129
	v_mov_b32_e32 v125, v129
	v_mov_b32_e32 v126, v129
	v_mov_b32_e32 v127, v129
	s_waitcnt vmcnt(0) lgkmcnt(0)
	s_barrier
	v_readfirstlane_b32 s48, v150
	s_sub_u32 s48, s48, 16
	s_mov_b32 s49, 0
	s_mov_b32 s50, 0x8000
	s_mov_b32 s52, 0x10000
	v_and_b32_e32 v170, 63, v186
	v_and_b32_e32 v171, 15, v170
	v_lshrrev_b32_e32 v166, 4, v170
	v_bfe_u32 v167, v170, 1, 3
	v_xor_b32_e32 v142, v166, v167
	v_or_b32_e32 v166, 4, v166
	v_xor_b32_e32 v143, v166, v167
	v_lshlrev_b32_e32 v142, 4, v142
	v_lshlrev_b32_e32 v143, 4, v143
	v_lshl_add_u32 v142, v171, 7, v142
	v_lshl_add_u32 v143, v171, 7, v143
	v_bfe_u32 v166, v186, 6, 2
	v_lshl_add_u32 v144, v166, 13, v142
	v_lshl_add_u32 v145, v166, 13, v143
	v_lshrrev_b32_e32 v166, 8, v186
	v_lshl_add_u32 v142, v166, 14, v142
	v_lshl_add_u32 v143, v166, 14, v143
	v_readfirstlane_b32 s56, v138
	v_readfirstlane_b32 s57, v139
	s_and_b32 s53, s48, 0x400
	s_lshr_b32 s53, s53, 4
	s_sub_u32 s56, s56, s53
	s_subb_u32 s57, s57, 0
	v_subrev_u32_e32 v168, s56, v138
	s_add_u32 s62, s56, s24
	s_addc_u32 s63, s57, s25
	s_add_u32 s60, s56, s22
	s_addc_u32 s61, s57, s23
	s_add_u32 s58, s56, s20
	s_addc_u32 s59, s57, s21
	s_add_u32 s56, s56, s18
	s_addc_u32 s57, s57, s19
	v_readfirstlane_b32 s64, v140
	v_readfirstlane_b32 s65, v141
	s_and_b32 s53, s48, 0x400
	s_lshr_b32 s53, s53, 4
	s_sub_u32 s64, s64, s53
	s_subb_u32 s65, s65, 0
	v_subrev_u32_e32 v169, s64, v140
	s_add_u32 s70, s64, s24
	s_addc_u32 s71, s65, s25
	s_add_u32 s68, s64, s22
	s_addc_u32 s69, s65, s23
	s_add_u32 s66, s64, s20
	s_addc_u32 s67, s65, s21
	s_add_u32 s64, s64, s18
	s_addc_u32 s65, s65, s19
	s_add_u32 m0, s52, s48
	s_nop 0
	global_load_lds_dwordx4 v168, s[56:57]
	s_add_u32 s56, s56, 0x80
	s_addc_u32 s57, s57, 0
	s_add_u32 s53, s52, s48
	s_add_u32 m0, s53, 0x2000
	s_nop 0
	global_load_lds_dwordx4 v168, s[58:59]
	s_add_u32 s58, s58, 0x80
	s_addc_u32 s59, s59, 0
	s_add_u32 s53, s52, s48
	s_add_u32 m0, s53, 0x4000
	s_nop 0
	global_load_lds_dwordx4 v168, s[60:61]
	s_add_u32 s60, s60, 0x80
	s_addc_u32 s61, s61, 0
	s_add_u32 s53, s52, s48
	s_add_u32 m0, s53, 0x6000
	s_nop 0
	global_load_lds_dwordx4 v168, s[62:63]
	s_add_u32 s62, s62, 0x80
	s_addc_u32 s63, s63, 0
	s_add_u32 s51, s50, 0x10000
	s_sub_u32 s53, s51, 0x28000
	s_cmp_ge_u32 s51, 0x28000
	s_cselect_b32 s51, s53, s51
	s_add_u32 m0, s51, s48
	s_nop 0
	global_load_lds_dwordx4 v169, s[64:65]
	s_add_u32 s64, s64, 0x80
	s_addc_u32 s65, s65, 0
	s_add_u32 s53, s51, s48
	s_add_u32 m0, s53, 0x2000
	s_nop 0
	global_load_lds_dwordx4 v169, s[66:67]
	s_add_u32 s66, s66, 0x80
	s_addc_u32 s67, s67, 0
	s_add_u32 s53, s51, s48
	s_add_u32 m0, s53, 0x4000
	s_nop 0
	global_load_lds_dwordx4 v169, s[68:69]
	s_add_u32 s68, s68, 0x80
	s_addc_u32 s69, s69, 0
	s_add_u32 s53, s51, s48
	s_add_u32 m0, s53, 0x6000
	s_nop 0
	global_load_lds_dwordx4 v169, s[70:71]
	s_add_u32 s70, s70, 0x80
	s_addc_u32 s71, s71, 0
	v_add_u32_e32 v167, s50, v144
	v_add_u32_e32 v166, s49, v142
	ds_read_b128 v[188:191], v167
	ds_read_b128 v[192:195], v167 offset:2048
	ds_read_b128 v[196:199], v167 offset:4096
	ds_read_b128 v[200:203], v167 offset:6144
	ds_read_b128 v[220:223], v166
	ds_read_b128 v[224:227], v166 offset:2048
	ds_read_b128 v[228:231], v166 offset:4096
	ds_read_b128 v[232:235], v166 offset:6144
	.p2align 6
.Lg162_loop:
	s_add_u32 s51, s50, 0x10000
	s_sub_u32 s53, s51, 0x28000
	s_cmp_ge_u32 s51, 0x28000
	s_cselect_b32 s51, s53, s51
	s_add_u32 s52, s49, 0x20000
	s_sub_u32 s53, s52, 0x28000
	s_cmp_ge_u32 s52, 0x28000
	s_cselect_b32 s52, s53, s52
	v_add_u32_e32 v167, s50, v145
	s_waitcnt lgkmcnt(4)
	s_waitcnt lgkmcnt(3)
	v_mfma_f32_16x16x32_bf16 v[112:115], v[188:191], v[220:223], v[112:115]
	v_mfma_f32_16x16x32_bf16 v[120:123], v[192:195], v[220:223], v[120:123]
	v_mfma_f32_16x16x32_bf16 v[96:99], v[196:199], v[220:223], v[96:99]
	v_mfma_f32_16x16x32_bf16 v[104:107], v[200:203], v[220:223], v[104:107]
	s_add_u32 m0, s52, s48
	s_nop 0
	global_load_lds_dwordx4 v168, s[56:57]
	s_add_u32 s56, s56, 0x80
	s_addc_u32 s57, s57, 0
	s_add_u32 s53, s52, s48
	s_add_u32 m0, s53, 0x2000
	s_nop 0
	global_load_lds_dwordx4 v168, s[58:59]
	s_add_u32 s58, s58, 0x80
	s_addc_u32 s59, s59, 0
	ds_read_b128 v[220:223], v166 offset:8192
	ds_read_b128 v[204:207], v167
	s_waitcnt lgkmcnt(4)
	v_mfma_f32_16x16x32_bf16 v[116:119], v[188:191], v[224:227], v[116:119]
	v_mfma_f32_16x16x32_bf16 v[124:127], v[192:195], v[224:227], v[124:127]
	v_mfma_f32_16x16x32_bf16 v[100:103], v[196:199], v[224:227], v[100:103]
	v_mfma_f32_16x16x32_bf16 v[108:111], v[200:203], v[224:227], v[108:111]
	s_add_u32 s53, s52, s48
	s_add_u32 m0, s53, 0x4000
	s_nop 0
	global_load_lds_dwordx4 v168, s[60:61]
	s_add_u32 s60, s60, 0x80
	s_addc_u32 s61, s61, 0
	s_add_u32 s53, s52, s48
	s_add_u32 m0, s53, 0x6000
	s_nop 0
	global_load_lds_dwordx4 v168, s[62:63]
	s_add_u32 s62, s62, 0x80
	s_addc_u32 s63, s63, 0
	ds_read_b128 v[224:227], v166 offset:10240
	ds_read_b128 v[208:211], v167 offset:2048
	s_waitcnt lgkmcnt(5)
	v_mfma_f32_16x16x32_bf16 v[80:83], v[188:191], v[228:231], v[80:83]
	v_mfma_f32_16x16x32_bf16 v[88:91], v[192:195], v[228:231], v[88:91]
	v_mfma_f32_16x16x32_bf16 v[64:67], v[196:199], v[228:231], v[64:67]
	v_mfma_f32_16x16x32_bf16 v[72:75], v[200:203], v[228:231], v[72:75]
	ds_read_b128 v[228:231], v166 offset:12288
	ds_read_b128 v[212:215], v167 offset:4096
	s_waitcnt lgkmcnt(6)
	v_mfma_f32_16x16x32_bf16 v[84:87], v[188:191], v[232:235], v[84:87]
	v_mfma_f32_16x16x32_bf16 v[92:95], v[192:195], v[232:235], v[92:95]
	v_mfma_f32_16x16x32_bf16 v[68:71], v[196:199], v[232:235], v[68:71]
	v_mfma_f32_16x16x32_bf16 v[76:79], v[200:203], v[232:235], v[76:79]
	ds_read_b128 v[232:235], v166 offset:14336
	ds_read_b128 v[216:219], v167 offset:6144
	v_add_u32_e32 v166, s49, v143
	s_waitcnt lgkmcnt(7)
	v_mfma_f32_16x16x32_bf16 v[48:51], v[188:191], v[220:223], v[48:51]
	v_mfma_f32_16x16x32_bf16 v[56:59], v[192:195], v[220:223], v[56:59]
	v_mfma_f32_16x16x32_bf16 v[32:35], v[196:199], v[220:223], v[32:35]
	v_mfma_f32_16x16x32_bf16 v[40:43], v[200:203], v[220:223], v[40:43]
	ds_read_b128 v[220:223], v166
	s_waitcnt lgkmcnt(6)
	v_mfma_f32_16x16x32_bf16 v[52:55], v[188:191], v[224:227], v[52:55]
	v_mfma_f32_16x16x32_bf16 v[60:63], v[192:195], v[224:227], v[60:63]
	v_mfma_f32_16x16x32_bf16 v[36:39], v[196:199], v[224:227], v[36:39]
	v_mfma_f32_16x16x32_bf16 v[44:47], v[200:203], v[224:227], v[44:47]
	ds_read_b128 v[224:227], v166 offset:2048
	s_waitcnt lgkmcnt(5)
	v_mfma_f32_16x16x32_bf16 v[16:19], v[188:191], v[228:231], v[16:19]
	v_mfma_f32_16x16x32_bf16 v[24:27], v[192:195], v[228:231], v[24:27]
	v_mfma_f32_16x16x32_bf16 v[0:3], v[196:199], v[228:231], v[0:3]
	v_mfma_f32_16x16x32_bf16 v[8:11], v[200:203], v[228:231], v[8:11]
	ds_read_b128 v[228:231], v166 offset:4096
	s_waitcnt lgkmcnt(4)
	v_mfma_f32_16x16x32_bf16 v[20:23], v[188:191], v[232:235], v[20:23]
	v_mfma_f32_16x16x32_bf16 v[28:31], v[192:195], v[232:235], v[28:31]
	v_mfma_f32_16x16x32_bf16 v[4:7], v[196:199], v[232:235], v[4:7]
	v_mfma_f32_16x16x32_bf16 v[12:15], v[200:203], v[232:235], v[12:15]
	ds_read_b128 v[232:235], v166 offset:6144
	s_waitcnt lgkmcnt(4)
	s_waitcnt lgkmcnt(3)
	v_mfma_f32_16x16x32_bf16 v[112:115], v[204:207], v[220:223], v[112:115]
	v_mfma_f32_16x16x32_bf16 v[120:123], v[208:211], v[220:223], v[120:123]
	v_mfma_f32_16x16x32_bf16 v[96:99], v[212:215], v[220:223], v[96:99]
	v_mfma_f32_16x16x32_bf16 v[104:107], v[216:219], v[220:223], v[104:107]
	ds_read_b128 v[220:223], v166 offset:8192
	s_waitcnt lgkmcnt(3)
	v_mfma_f32_16x16x32_bf16 v[116:119], v[204:207], v[224:227], v[116:119]
	v_mfma_f32_16x16x32_bf16 v[124:127], v[208:211], v[224:227], v[124:127]
	v_mfma_f32_16x16x32_bf16 v[100:103], v[212:215], v[224:227], v[100:103]
	v_mfma_f32_16x16x32_bf16 v[108:111], v[216:219], v[224:227], v[108:111]
	ds_read_b128 v[224:227], v166 offset:10240
	s_waitcnt lgkmcnt(3)
	v_mfma_f32_16x16x32_bf16 v[80:83], v[204:207], v[228:231], v[80:83]
	v_mfma_f32_16x16x32_bf16 v[88:91], v[208:211], v[228:231], v[88:91]
	v_mfma_f32_16x16x32_bf16 v[64:67], v[212:215], v[228:231], v[64:67]
	v_mfma_f32_16x16x32_bf16 v[72:75], v[216:219], v[228:231], v[72:75]
	ds_read_b128 v[228:231], v166 offset:12288
	s_waitcnt lgkmcnt(3)
	v_mfma_f32_16x16x32_bf16 v[84:87], v[204:207], v[232:235], v[84:87]
	v_mfma_f32_16x16x32_bf16 v[92:95], v[208:211], v[232:235], v[92:95]
	v_mfma_f32_16x16x32_bf16 v[68:71], v[212:215], v[232:235], v[68:71]
	v_mfma_f32_16x16x32_bf16 v[76:79], v[216:219], v[232:235], v[76:79]
	ds_read_b128 v[232:235], v166 offset:14336
	s_waitcnt lgkmcnt(3)
	v_mfma_f32_16x16x32_bf16 v[48:51], v[204:207], v[220:223], v[48:51]
	v_mfma_f32_16x16x32_bf16 v[56:59], v[208:211], v[220:223], v[56:59]
	v_mfma_f32_16x16x32_bf16 v[32:35], v[212:215], v[220:223], v[32:35]
	v_mfma_f32_16x16x32_bf16 v[40:43], v[216:219], v[220:223], v[40:43]
	s_waitcnt lgkmcnt(2)
	v_mfma_f32_16x16x32_bf16 v[52:55], v[204:207], v[224:227], v[52:55]
	v_mfma_f32_16x16x32_bf16 v[60:63], v[208:211], v[224:227], v[60:63]
	v_mfma_f32_16x16x32_bf16 v[36:39], v[212:215], v[224:227], v[36:39]
	v_mfma_f32_16x16x32_bf16 v[44:47], v[216:219], v[224:227], v[44:47]
	s_waitcnt lgkmcnt(1)
	v_mfma_f32_16x16x32_bf16 v[16:19], v[204:207], v[228:231], v[16:19]
	v_mfma_f32_16x16x32_bf16 v[24:27], v[208:211], v[228:231], v[24:27]
	v_mfma_f32_16x16x32_bf16 v[0:3], v[212:215], v[228:231], v[0:3]
	v_mfma_f32_16x16x32_bf16 v[8:11], v[216:219], v[228:231], v[8:11]
	s_waitcnt lgkmcnt(0)
	s_add_u32 s28, s28, 0x80
	s_addc_u32 s29, s29, 0
	s_add_u32 s49, s49, 0x10000
	s_sub_u32 s53, s49, 0x28000
	s_cmp_ge_u32 s49, 0x28000
	s_cselect_b32 s49, s53, s49
	s_mov_b32 s50, s51
	s_waitcnt vmcnt(4)
	s_barrier
	v_add_u32_e32 v167, s50, v144
	v_add_u32_e32 v166, s49, v142
	ds_read_b128 v[188:191], v167
	ds_read_b128 v[192:195], v167 offset:2048
	ds_read_b128 v[196:199], v167 offset:4096
	ds_read_b128 v[200:203], v167 offset:6144
	ds_read_b128 v[220:223], v166
	ds_read_b128 v[224:227], v166 offset:2048
	ds_read_b128 v[228:231], v166 offset:4096
	s_add_u32 s51, s50, 0x10000
	s_sub_u32 s53, s51, 0x28000
	s_cmp_ge_u32 s51, 0x28000
	s_cselect_b32 s51, s53, s51
	s_add_u32 m0, s51, s48
	s_nop 0
	global_load_lds_dwordx4 v169, s[64:65]
	s_add_u32 s64, s64, 0x80
	s_addc_u32 s65, s65, 0
	s_add_u32 s53, s51, s48
	s_add_u32 m0, s53, 0x2000
	s_nop 0
	global_load_lds_dwordx4 v169, s[66:67]
	s_add_u32 s66, s66, 0x80
	s_addc_u32 s67, s67, 0
	s_add_u32 s53, s51, s48
	s_add_u32 m0, s53, 0x4000
	s_nop 0
	global_load_lds_dwordx4 v169, s[68:69]
	s_add_u32 s68, s68, 0x80
	s_addc_u32 s69, s69, 0
	s_add_u32 s53, s51, s48
	s_add_u32 m0, s53, 0x6000
	s_nop 0
	global_load_lds_dwordx4 v169, s[70:71]
	s_add_u32 s70, s70, 0x80
	s_addc_u32 s71, s71, 0
	v_mfma_f32_16x16x32_bf16 v[20:23], v[204:207], v[232:235], v[20:23]
	v_mfma_f32_16x16x32_bf16 v[28:31], v[208:211], v[232:235], v[28:31]
	v_mfma_f32_16x16x32_bf16 v[4:7], v[212:215], v[232:235], v[4:7]
	v_mfma_f32_16x16x32_bf16 v[12:15], v[216:219], v[232:235], v[12:15]
	ds_read_b128 v[232:235], v166 offset:6144
	s_cmpk_lg_i32 s28, 0xf00
	s_cbranch_scc1 .Lg162_loop
	s_add_u32 s51, s50, 0x10000
	s_sub_u32 s53, s51, 0x28000
	s_cmp_ge_u32 s51, 0x28000
	s_cselect_b32 s51, s53, s51
	v_add_u32_e32 v167, s50, v145
	s_waitcnt lgkmcnt(4)
	s_waitcnt lgkmcnt(3)
	v_mfma_f32_16x16x32_bf16 v[112:115], v[188:191], v[220:223], v[112:115]
	v_mfma_f32_16x16x32_bf16 v[120:123], v[192:195], v[220:223], v[120:123]
	v_mfma_f32_16x16x32_bf16 v[96:99], v[196:199], v[220:223], v[96:99]
	v_mfma_f32_16x16x32_bf16 v[104:107], v[200:203], v[220:223], v[104:107]
	ds_read_b128 v[220:223], v166 offset:8192
	ds_read_b128 v[204:207], v167
	s_waitcnt lgkmcnt(4)
	v_mfma_f32_16x16x32_bf16 v[116:119], v[188:191], v[224:227], v[116:119]
	v_mfma_f32_16x16x32_bf16 v[124:127], v[192:195], v[224:227], v[124:127]
	v_mfma_f32_16x16x32_bf16 v[100:103], v[196:199], v[224:227], v[100:103]
	v_mfma_f32_16x16x32_bf16 v[108:111], v[200:203], v[224:227], v[108:111]
	ds_read_b128 v[224:227], v166 offset:10240
	ds_read_b128 v[208:211], v167 offset:2048
	s_waitcnt lgkmcnt(5)
	v_mfma_f32_16x16x32_bf16 v[80:83], v[188:191], v[228:231], v[80:83]
	v_mfma_f32_16x16x32_bf16 v[88:91], v[192:195], v[228:231], v[88:91]
	v_mfma_f32_16x16x32_bf16 v[64:67], v[196:199], v[228:231], v[64:67]
	v_mfma_f32_16x16x32_bf16 v[72:75], v[200:203], v[228:231], v[72:75]
	ds_read_b128 v[228:231], v166 offset:12288
	ds_read_b128 v[212:215], v167 offset:4096
	s_waitcnt lgkmcnt(6)
	v_mfma_f32_16x16x32_bf16 v[84:87], v[188:191], v[232:235], v[84:87]
	v_mfma_f32_16x16x32_bf16 v[92:95], v[192:195], v[232:235], v[92:95]
	v_mfma_f32_16x16x32_bf16 v[68:71], v[196:199], v[232:235], v[68:71]
	v_mfma_f32_16x16x32_bf16 v[76:79], v[200:203], v[232:235], v[76:79]
	ds_read_b128 v[232:235], v166 offset:14336
	ds_read_b128 v[216:219], v167 offset:6144
	v_add_u32_e32 v166, s49, v143
	s_waitcnt lgkmcnt(7)
	v_mfma_f32_16x16x32_bf16 v[48:51], v[188:191], v[220:223], v[48:51]
	v_mfma_f32_16x16x32_bf16 v[56:59], v[192:195], v[220:223], v[56:59]
	v_mfma_f32_16x16x32_bf16 v[32:35], v[196:199], v[220:223], v[32:35]
	v_mfma_f32_16x16x32_bf16 v[40:43], v[200:203], v[220:223], v[40:43]
	ds_read_b128 v[220:223], v166
	s_waitcnt lgkmcnt(6)
	v_mfma_f32_16x16x32_bf16 v[52:55], v[188:191], v[224:227], v[52:55]
	v_mfma_f32_16x16x32_bf16 v[60:63], v[192:195], v[224:227], v[60:63]
	v_mfma_f32_16x16x32_bf16 v[36:39], v[196:199], v[224:227], v[36:39]
	v_mfma_f32_16x16x32_bf16 v[44:47], v[200:203], v[224:227], v[44:47]
	ds_read_b128 v[224:227], v166 offset:2048
	s_waitcnt lgkmcnt(5)
	v_mfma_f32_16x16x32_bf16 v[16:19], v[188:191], v[228:231], v[16:19]
	v_mfma_f32_16x16x32_bf16 v[24:27], v[192:195], v[228:231], v[24:27]
	v_mfma_f32_16x16x32_bf16 v[0:3], v[196:199], v[228:231], v[0:3]
	v_mfma_f32_16x16x32_bf16 v[8:11], v[200:203], v[228:231], v[8:11]
	ds_read_b128 v[228:231], v166 offset:4096
	s_waitcnt lgkmcnt(4)
	v_mfma_f32_16x16x32_bf16 v[20:23], v[188:191], v[232:235], v[20:23]
	v_mfma_f32_16x16x32_bf16 v[28:31], v[192:195], v[232:235], v[28:31]
	v_mfma_f32_16x16x32_bf16 v[4:7], v[196:199], v[232:235], v[4:7]
	v_mfma_f32_16x16x32_bf16 v[12:15], v[200:203], v[232:235], v[12:15]
	ds_read_b128 v[232:235], v166 offset:6144
	s_waitcnt lgkmcnt(4)
	s_waitcnt lgkmcnt(3)
	v_mfma_f32_16x16x32_bf16 v[112:115], v[204:207], v[220:223], v[112:115]
	v_mfma_f32_16x16x32_bf16 v[120:123], v[208:211], v[220:223], v[120:123]
	v_mfma_f32_16x16x32_bf16 v[96:99], v[212:215], v[220:223], v[96:99]
	v_mfma_f32_16x16x32_bf16 v[104:107], v[216:219], v[220:223], v[104:107]
	ds_read_b128 v[220:223], v166 offset:8192
	s_waitcnt lgkmcnt(3)
	v_mfma_f32_16x16x32_bf16 v[116:119], v[204:207], v[224:227], v[116:119]
	v_mfma_f32_16x16x32_bf16 v[124:127], v[208:211], v[224:227], v[124:127]
	v_mfma_f32_16x16x32_bf16 v[100:103], v[212:215], v[224:227], v[100:103]
	v_mfma_f32_16x16x32_bf16 v[108:111], v[216:219], v[224:227], v[108:111]
	ds_read_b128 v[224:227], v166 offset:10240
	s_waitcnt lgkmcnt(3)
	v_mfma_f32_16x16x32_bf16 v[80:83], v[204:207], v[228:231], v[80:83]
	v_mfma_f32_16x16x32_bf16 v[88:91], v[208:211], v[228:231], v[88:91]
	v_mfma_f32_16x16x32_bf16 v[64:67], v[212:215], v[228:231], v[64:67]
	v_mfma_f32_16x16x32_bf16 v[72:75], v[216:219], v[228:231], v[72:75]
	ds_read_b128 v[228:231], v166 offset:12288
	s_waitcnt lgkmcnt(3)
	v_mfma_f32_16x16x32_bf16 v[84:87], v[204:207], v[232:235], v[84:87]
	v_mfma_f32_16x16x32_bf16 v[92:95], v[208:211], v[232:235], v[92:95]
	v_mfma_f32_16x16x32_bf16 v[68:71], v[212:215], v[232:235], v[68:71]
	v_mfma_f32_16x16x32_bf16 v[76:79], v[216:219], v[232:235], v[76:79]
	ds_read_b128 v[232:235], v166 offset:14336
	s_waitcnt lgkmcnt(3)
	v_mfma_f32_16x16x32_bf16 v[48:51], v[204:207], v[220:223], v[48:51]
	v_mfma_f32_16x16x32_bf16 v[56:59], v[208:211], v[220:223], v[56:59]
	v_mfma_f32_16x16x32_bf16 v[32:35], v[212:215], v[220:223], v[32:35]
	v_mfma_f32_16x16x32_bf16 v[40:43], v[216:219], v[220:223], v[40:43]
	s_waitcnt lgkmcnt(2)
	v_mfma_f32_16x16x32_bf16 v[52:55], v[204:207], v[224:227], v[52:55]
	v_mfma_f32_16x16x32_bf16 v[60:63], v[208:211], v[224:227], v[60:63]
	v_mfma_f32_16x16x32_bf16 v[36:39], v[212:215], v[224:227], v[36:39]
	v_mfma_f32_16x16x32_bf16 v[44:47], v[216:219], v[224:227], v[44:47]
	s_waitcnt lgkmcnt(1)
	v_mfma_f32_16x16x32_bf16 v[16:19], v[204:207], v[228:231], v[16:19]
	v_mfma_f32_16x16x32_bf16 v[24:27], v[208:211], v[228:231], v[24:27]
	v_mfma_f32_16x16x32_bf16 v[0:3], v[212:215], v[228:231], v[0:3]
	v_mfma_f32_16x16x32_bf16 v[8:11], v[216:219], v[228:231], v[8:11]
	s_waitcnt lgkmcnt(0)
	s_add_u32 s28, s28, 0x80
	s_addc_u32 s29, s29, 0
	s_add_u32 s49, s49, 0x10000
	s_sub_u32 s53, s49, 0x28000
	s_cmp_ge_u32 s49, 0x28000
	s_cselect_b32 s49, s53, s49
	s_mov_b32 s50, s51
	s_waitcnt vmcnt(0)
	s_barrier
	v_add_u32_e32 v167, s50, v144
	v_add_u32_e32 v166, s49, v142
	ds_read_b128 v[188:191], v167
	ds_read_b128 v[192:195], v167 offset:2048
	ds_read_b128 v[196:199], v167 offset:4096
	ds_read_b128 v[200:203], v167 offset:6144
	ds_read_b128 v[220:223], v166
	ds_read_b128 v[224:227], v166 offset:2048
	ds_read_b128 v[228:231], v166 offset:4096
	v_mfma_f32_16x16x32_bf16 v[20:23], v[204:207], v[232:235], v[20:23]
	v_mfma_f32_16x16x32_bf16 v[28:31], v[208:211], v[232:235], v[28:31]
	v_mfma_f32_16x16x32_bf16 v[4:7], v[212:215], v[232:235], v[4:7]
	v_mfma_f32_16x16x32_bf16 v[12:15], v[216:219], v[232:235], v[12:15]
	ds_read_b128 v[232:235], v166 offset:6144
	v_add_u32_e32 v167, s50, v145
	s_waitcnt lgkmcnt(4)
	s_waitcnt lgkmcnt(3)
	v_mfma_f32_16x16x32_bf16 v[112:115], v[188:191], v[220:223], v[112:115]
	v_mfma_f32_16x16x32_bf16 v[120:123], v[192:195], v[220:223], v[120:123]
	v_mfma_f32_16x16x32_bf16 v[96:99], v[196:199], v[220:223], v[96:99]
	v_mfma_f32_16x16x32_bf16 v[104:107], v[200:203], v[220:223], v[104:107]
	ds_read_b128 v[220:223], v166 offset:8192
	ds_read_b128 v[204:207], v167
	s_waitcnt lgkmcnt(4)
	v_mfma_f32_16x16x32_bf16 v[116:119], v[188:191], v[224:227], v[116:119]
	v_mfma_f32_16x16x32_bf16 v[124:127], v[192:195], v[224:227], v[124:127]
	v_mfma_f32_16x16x32_bf16 v[100:103], v[196:199], v[224:227], v[100:103]
	v_mfma_f32_16x16x32_bf16 v[108:111], v[200:203], v[224:227], v[108:111]
	ds_read_b128 v[224:227], v166 offset:10240
	ds_read_b128 v[208:211], v167 offset:2048
	s_waitcnt lgkmcnt(5)
	v_mfma_f32_16x16x32_bf16 v[80:83], v[188:191], v[228:231], v[80:83]
	v_mfma_f32_16x16x32_bf16 v[88:91], v[192:195], v[228:231], v[88:91]
	v_mfma_f32_16x16x32_bf16 v[64:67], v[196:199], v[228:231], v[64:67]
	v_mfma_f32_16x16x32_bf16 v[72:75], v[200:203], v[228:231], v[72:75]
	ds_read_b128 v[228:231], v166 offset:12288
	ds_read_b128 v[212:215], v167 offset:4096
	s_waitcnt lgkmcnt(6)
	v_mfma_f32_16x16x32_bf16 v[84:87], v[188:191], v[232:235], v[84:87]
	v_mfma_f32_16x16x32_bf16 v[92:95], v[192:195], v[232:235], v[92:95]
	v_mfma_f32_16x16x32_bf16 v[68:71], v[196:199], v[232:235], v[68:71]
	v_mfma_f32_16x16x32_bf16 v[76:79], v[200:203], v[232:235], v[76:79]
	ds_read_b128 v[232:235], v166 offset:14336
	ds_read_b128 v[216:219], v167 offset:6144
	v_add_u32_e32 v166, s49, v143
	s_waitcnt lgkmcnt(7)
	v_mfma_f32_16x16x32_bf16 v[48:51], v[188:191], v[220:223], v[48:51]
	v_mfma_f32_16x16x32_bf16 v[56:59], v[192:195], v[220:223], v[56:59]
	v_mfma_f32_16x16x32_bf16 v[32:35], v[196:199], v[220:223], v[32:35]
	v_mfma_f32_16x16x32_bf16 v[40:43], v[200:203], v[220:223], v[40:43]
	ds_read_b128 v[220:223], v166
	s_waitcnt lgkmcnt(6)
	v_mfma_f32_16x16x32_bf16 v[52:55], v[188:191], v[224:227], v[52:55]
	v_mfma_f32_16x16x32_bf16 v[60:63], v[192:195], v[224:227], v[60:63]
	v_mfma_f32_16x16x32_bf16 v[36:39], v[196:199], v[224:227], v[36:39]
	v_mfma_f32_16x16x32_bf16 v[44:47], v[200:203], v[224:227], v[44:47]
	ds_read_b128 v[224:227], v166 offset:2048
	s_waitcnt lgkmcnt(5)
	v_mfma_f32_16x16x32_bf16 v[16:19], v[188:191], v[228:231], v[16:19]
	v_mfma_f32_16x16x32_bf16 v[24:27], v[192:195], v[228:231], v[24:27]
	v_mfma_f32_16x16x32_bf16 v[0:3], v[196:199], v[228:231], v[0:3]
	v_mfma_f32_16x16x32_bf16 v[8:11], v[200:203], v[228:231], v[8:11]
	ds_read_b128 v[228:231], v166 offset:4096
	s_waitcnt lgkmcnt(4)
	v_mfma_f32_16x16x32_bf16 v[20:23], v[188:191], v[232:235], v[20:23]
	v_mfma_f32_16x16x32_bf16 v[28:31], v[192:195], v[232:235], v[28:31]
	v_mfma_f32_16x16x32_bf16 v[4:7], v[196:199], v[232:235], v[4:7]
	v_mfma_f32_16x16x32_bf16 v[12:15], v[200:203], v[232:235], v[12:15]
	ds_read_b128 v[232:235], v166 offset:6144
	s_waitcnt lgkmcnt(4)
	s_waitcnt lgkmcnt(3)
	v_mfma_f32_16x16x32_bf16 v[112:115], v[204:207], v[220:223], v[112:115]
	v_mfma_f32_16x16x32_bf16 v[120:123], v[208:211], v[220:223], v[120:123]
	v_mfma_f32_16x16x32_bf16 v[96:99], v[212:215], v[220:223], v[96:99]
	v_mfma_f32_16x16x32_bf16 v[104:107], v[216:219], v[220:223], v[104:107]
	ds_read_b128 v[220:223], v166 offset:8192
	s_waitcnt lgkmcnt(3)
	v_mfma_f32_16x16x32_bf16 v[116:119], v[204:207], v[224:227], v[116:119]
	v_mfma_f32_16x16x32_bf16 v[124:127], v[208:211], v[224:227], v[124:127]
	v_mfma_f32_16x16x32_bf16 v[100:103], v[212:215], v[224:227], v[100:103]
	v_mfma_f32_16x16x32_bf16 v[108:111], v[216:219], v[224:227], v[108:111]
	ds_read_b128 v[224:227], v166 offset:10240
	s_waitcnt lgkmcnt(3)
	v_mfma_f32_16x16x32_bf16 v[80:83], v[204:207], v[228:231], v[80:83]
	v_mfma_f32_16x16x32_bf16 v[88:91], v[208:211], v[228:231], v[88:91]
	v_mfma_f32_16x16x32_bf16 v[64:67], v[212:215], v[228:231], v[64:67]
	v_mfma_f32_16x16x32_bf16 v[72:75], v[216:219], v[228:231], v[72:75]
	ds_read_b128 v[228:231], v166 offset:12288
	s_waitcnt lgkmcnt(3)
	v_mfma_f32_16x16x32_bf16 v[84:87], v[204:207], v[232:235], v[84:87]
	v_mfma_f32_16x16x32_bf16 v[92:95], v[208:211], v[232:235], v[92:95]
	v_mfma_f32_16x16x32_bf16 v[68:71], v[212:215], v[232:235], v[68:71]
	v_mfma_f32_16x16x32_bf16 v[76:79], v[216:219], v[232:235], v[76:79]
	ds_read_b128 v[232:235], v166 offset:14336
	s_waitcnt lgkmcnt(3)
	v_mfma_f32_16x16x32_bf16 v[48:51], v[204:207], v[220:223], v[48:51]
	v_mfma_f32_16x16x32_bf16 v[56:59], v[208:211], v[220:223], v[56:59]
	v_mfma_f32_16x16x32_bf16 v[32:35], v[212:215], v[220:223], v[32:35]
	v_mfma_f32_16x16x32_bf16 v[40:43], v[216:219], v[220:223], v[40:43]
	s_waitcnt lgkmcnt(2)
	v_mfma_f32_16x16x32_bf16 v[52:55], v[204:207], v[224:227], v[52:55]
	v_mfma_f32_16x16x32_bf16 v[60:63], v[208:211], v[224:227], v[60:63]
	v_mfma_f32_16x16x32_bf16 v[36:39], v[212:215], v[224:227], v[36:39]
	v_mfma_f32_16x16x32_bf16 v[44:47], v[216:219], v[224:227], v[44:47]
	s_waitcnt lgkmcnt(1)
	v_mfma_f32_16x16x32_bf16 v[16:19], v[204:207], v[228:231], v[16:19]
	v_mfma_f32_16x16x32_bf16 v[24:27], v[208:211], v[228:231], v[24:27]
	v_mfma_f32_16x16x32_bf16 v[0:3], v[212:215], v[228:231], v[0:3]
	v_mfma_f32_16x16x32_bf16 v[8:11], v[216:219], v[228:231], v[8:11]
	s_waitcnt lgkmcnt(0)
	s_waitcnt vmcnt(0)
	s_barrier
	v_mfma_f32_16x16x32_bf16 v[20:23], v[204:207], v[232:235], v[20:23]
	v_mfma_f32_16x16x32_bf16 v[28:31], v[208:211], v[232:235], v[28:31]
	v_mfma_f32_16x16x32_bf16 v[4:7], v[212:215], v[232:235], v[4:7]
	v_mfma_f32_16x16x32_bf16 v[12:15], v[216:219], v[232:235], v[12:15]
	s_nop 15
	v_permlane16_swap_b32_e32 v112, v116
	v_permlane16_swap_b32_e32 v113, v117
	v_permlane16_swap_b32_e32 v114, v118
	v_permlane16_swap_b32_e32 v115, v119
	v_permlane16_swap_b32_e32 v120, v124
	v_permlane16_swap_b32_e32 v121, v125
	v_permlane16_swap_b32_e32 v122, v126
	v_permlane16_swap_b32_e32 v123, v127
	v_permlane16_swap_b32_e32 v96, v100
	v_permlane16_swap_b32_e32 v97, v101
	v_permlane16_swap_b32_e32 v98, v102
	v_permlane16_swap_b32_e32 v99, v103
	v_permlane16_swap_b32_e32 v104, v108
	v_permlane16_swap_b32_e32 v105, v109
	v_permlane16_swap_b32_e32 v106, v110
	v_permlane16_swap_b32_e32 v107, v111
	v_permlane16_swap_b32_e32 v80, v84
	v_permlane16_swap_b32_e32 v81, v85
	v_permlane16_swap_b32_e32 v82, v86
	v_permlane16_swap_b32_e32 v83, v87
	v_permlane16_swap_b32_e32 v88, v92
	v_permlane16_swap_b32_e32 v89, v93
	v_permlane16_swap_b32_e32 v90, v94
	v_permlane16_swap_b32_e32 v91, v95
	v_permlane16_swap_b32_e32 v64, v68
	v_permlane16_swap_b32_e32 v65, v69
	v_permlane16_swap_b32_e32 v66, v70
	v_permlane16_swap_b32_e32 v67, v71
	v_permlane16_swap_b32_e32 v72, v76
	v_permlane16_swap_b32_e32 v73, v77
	v_permlane16_swap_b32_e32 v74, v78
	v_permlane16_swap_b32_e32 v75, v79
	v_permlane16_swap_b32_e32 v48, v52
	v_permlane16_swap_b32_e32 v49, v53
	v_permlane16_swap_b32_e32 v50, v54
	v_permlane16_swap_b32_e32 v51, v55
	v_permlane16_swap_b32_e32 v56, v60
	v_permlane16_swap_b32_e32 v57, v61
	v_permlane16_swap_b32_e32 v58, v62
	v_permlane16_swap_b32_e32 v59, v63
	v_permlane16_swap_b32_e32 v32, v36
	v_permlane16_swap_b32_e32 v33, v37
	v_permlane16_swap_b32_e32 v34, v38
	v_permlane16_swap_b32_e32 v35, v39
	v_permlane16_swap_b32_e32 v40, v44
	v_permlane16_swap_b32_e32 v41, v45
	v_permlane16_swap_b32_e32 v42, v46
	v_permlane16_swap_b32_e32 v43, v47
	v_permlane16_swap_b32_e32 v16, v20
	v_permlane16_swap_b32_e32 v17, v21
	v_permlane16_swap_b32_e32 v18, v22
	v_permlane16_swap_b32_e32 v19, v23
	v_permlane16_swap_b32_e32 v24, v28
	v_permlane16_swap_b32_e32 v25, v29
	v_permlane16_swap_b32_e32 v26, v30
	v_permlane16_swap_b32_e32 v27, v31
	v_permlane16_swap_b32_e32 v0, v4
	v_permlane16_swap_b32_e32 v1, v5
	v_permlane16_swap_b32_e32 v2, v6
	v_permlane16_swap_b32_e32 v3, v7
	v_permlane16_swap_b32_e32 v8, v12
	v_permlane16_swap_b32_e32 v9, v13
	v_permlane16_swap_b32_e32 v10, v14
	v_permlane16_swap_b32_e32 v11, v15
	v_permlane32_swap_b32_e32 v112, v116
	v_permlane32_swap_b32_e32 v113, v117
	v_permlane32_swap_b32_e32 v114, v118
	v_permlane32_swap_b32_e32 v115, v119
	v_permlane32_swap_b32_e32 v120, v124
	v_permlane32_swap_b32_e32 v121, v125
	v_permlane32_swap_b32_e32 v122, v126
	v_permlane32_swap_b32_e32 v123, v127
	v_permlane32_swap_b32_e32 v96, v100
	v_permlane32_swap_b32_e32 v97, v101
	v_permlane32_swap_b32_e32 v98, v102
	v_permlane32_swap_b32_e32 v99, v103
	v_permlane32_swap_b32_e32 v104, v108
	v_permlane32_swap_b32_e32 v105, v109
	v_permlane32_swap_b32_e32 v106, v110
	v_permlane32_swap_b32_e32 v107, v111
	v_permlane32_swap_b32_e32 v80, v84
	v_permlane32_swap_b32_e32 v81, v85
	v_permlane32_swap_b32_e32 v82, v86
	v_permlane32_swap_b32_e32 v83, v87
	v_permlane32_swap_b32_e32 v88, v92
	v_permlane32_swap_b32_e32 v89, v93
	v_permlane32_swap_b32_e32 v90, v94
	v_permlane32_swap_b32_e32 v91, v95
	v_permlane32_swap_b32_e32 v64, v68
	v_permlane32_swap_b32_e32 v65, v69
	v_permlane32_swap_b32_e32 v66, v70
	v_permlane32_swap_b32_e32 v67, v71
	v_permlane32_swap_b32_e32 v72, v76
	v_permlane32_swap_b32_e32 v73, v77
	v_permlane32_swap_b32_e32 v74, v78
	v_permlane32_swap_b32_e32 v75, v79
	v_permlane32_swap_b32_e32 v48, v52
	v_permlane32_swap_b32_e32 v49, v53
	v_permlane32_swap_b32_e32 v50, v54
	v_permlane32_swap_b32_e32 v51, v55
	v_permlane32_swap_b32_e32 v56, v60
	v_permlane32_swap_b32_e32 v57, v61
	v_permlane32_swap_b32_e32 v58, v62
	v_permlane32_swap_b32_e32 v59, v63
	v_permlane32_swap_b32_e32 v32, v36
	v_permlane32_swap_b32_e32 v33, v37
	v_permlane32_swap_b32_e32 v34, v38
	v_permlane32_swap_b32_e32 v35, v39
	v_permlane32_swap_b32_e32 v40, v44
	v_permlane32_swap_b32_e32 v41, v45
	v_permlane32_swap_b32_e32 v42, v46
	v_permlane32_swap_b32_e32 v43, v47
	v_permlane32_swap_b32_e32 v16, v20
	v_permlane32_swap_b32_e32 v17, v21
	v_permlane32_swap_b32_e32 v18, v22
	v_permlane32_swap_b32_e32 v19, v23
	v_permlane32_swap_b32_e32 v24, v28
	v_permlane32_swap_b32_e32 v25, v29
	v_permlane32_swap_b32_e32 v26, v30
	v_permlane32_swap_b32_e32 v27, v31
	v_permlane32_swap_b32_e32 v0, v4
	v_permlane32_swap_b32_e32 v1, v5
	v_permlane32_swap_b32_e32 v2, v6
	v_permlane32_swap_b32_e32 v3, v7
	v_permlane32_swap_b32_e32 v8, v12
	v_permlane32_swap_b32_e32 v9, v13
	v_permlane32_swap_b32_e32 v10, v14
	v_permlane32_swap_b32_e32 v11, v15
	s_nop 1
	s_branch .LBB0_163

.LBB0_198:
	s_ashr_i32 s27, s30, 2
	s_and_b32 s27, s27, -8
	s_or_b32 s33, s27, s3
	s_ashr_i32 s27, s33, 31
	s_lshr_b32 s27, s27, 29
	s_add_i32 s27, s33, s27
	s_ashr_i32 s46, s27, 3
	s_bfe_u32 s26, s30, 0x20003
	s_and_b32 s27, s27, 0x1ffff8
	s_lshl_b32 s47, s46, 2
	s_lshl_b32 s29, s26, 8
	s_sub_i32 s27, s33, s27
	s_or_b32 s26, s47, s26
	s_lshl_b32 s47, s30, 8
	s_lshl_b32 s27, s27, 11
	s_and_b32 s47, s47, 0x700
	s_or_b32 s27, s27, s47
	v_add_u32_e32 v0, s27, v142
	v_ashrrev_i32_e32 v1, 31, v0
	v_lshl_add_u32 v2, s26, 8, v142
	v_lshlrev_b64 v[0:1], 12, v[0:1]
	v_ashrrev_i32_e32 v3, 31, v2
	v_readfirstlane_b32 s47, v143
	v_add_u32_e32 v4, 0x8000, v143
	v_lshl_add_u64 v[0:1], v[130:131], 0, v[0:1]
	v_lshlrev_b64 v[2:3], 12, v[2:3]
	s_add_i32 m0, s47, -16
	v_readfirstlane_b32 s47, v4
	v_add_u32_e32 v6, 0x2000, v143
	v_lshl_add_u64 v[2:3], v[132:133], 0, v[2:3]
	global_load_lds_dwordx4 v[0:1], off
	s_add_i32 m0, s47, -16
	v_readfirstlane_b32 s47, v6
	v_add_u32_e32 v6, 0xa000, v143
	global_load_lds_dwordx4 v[2:3], off
	v_lshl_add_u64 v[4:5], v[0:1], 0, s[12:13]
	s_add_i32 m0, s47, -16
	v_readfirstlane_b32 s47, v6
	v_add_u32_e32 v6, 0x4000, v143
	global_load_lds_dwordx4 v[4:5], off
	v_lshl_add_u64 v[4:5], v[2:3], 0, s[12:13]
	s_add_i32 m0, s47, -16
	v_readfirstlane_b32 s47, v6
	v_add_u32_e32 v6, 0xc000, v143
	global_load_lds_dwordx4 v[4:5], off
	v_lshl_add_u64 v[4:5], v[0:1], 0, s[14:15]
	s_add_i32 m0, s47, -16
	v_readfirstlane_b32 s47, v6
	global_load_lds_dwordx4 v[4:5], off
	v_lshl_add_u64 v[4:5], v[2:3], 0, s[14:15]
	s_add_i32 m0, s47, -16
	v_lshl_add_u64 v[0:1], v[0:1], 0, s[16:17]
	global_load_lds_dwordx4 v[4:5], off
	v_add_u32_e32 v4, 0x6000, v143
	s_and_b32 s28, s34, 0x700
	v_readfirstlane_b32 s47, v4
	s_add_i32 m0, s47, -16
	s_lshl_b32 s33, s33, 11
	global_load_lds_dwordx4 v[0:1], off
	v_lshl_add_u64 v[0:1], v[2:3], 0, s[16:17]
	v_add_u32_e32 v2, 0xe000, v143
	s_or_b32 s28, s28, s33
	v_readfirstlane_b32 s47, v2
	s_add_i32 m0, s47, -16
	v_mov_b32_e32 v2, v129
	global_load_lds_dwordx4 v[0:1], off
	v_add_u32_e32 v0, s28, v142
	s_lshl_b32 s28, s46, 14
	v_subrev_u32_e32 v0, s28, v0
	v_ashrrev_i32_e32 v1, 31, v0
	s_lshl_b32 s28, s46, 10
	v_lshlrev_b64 v[0:1], 12, v[0:1]
	s_or_b32 s28, s29, s28
	v_lshl_add_u64 v[138:139], v[134:135], 0, v[0:1]
	v_add_u32_e32 v0, s28, v142
	v_ashrrev_i32_e32 v1, 31, v0
	v_lshlrev_b64 v[0:1], 12, v[0:1]
	v_lshl_add_u64 v[140:141], v[136:137], 0, v[0:1]
	s_mov_b64 s[28:29], 0
	s_mov_b32 s46, 0
	v_mov_b32_e32 v0, 0
	v_mov_b32_e32 v1, v129
	v_mov_b32_e32 v3, v129
	v_mov_b32_e32 v4, v129
	v_mov_b32_e32 v5, v129
	v_mov_b32_e32 v6, v129
	v_mov_b32_e32 v7, v129
	v_mov_b32_e32 v8, v129
	v_mov_b32_e32 v9, v129
	v_mov_b32_e32 v10, v129
	v_mov_b32_e32 v11, v129
	v_mov_b32_e32 v12, v129
	v_mov_b32_e32 v13, v129
	v_mov_b32_e32 v14, v129
	v_mov_b32_e32 v15, v129
	v_mov_b32_e32 v16, 0
	v_mov_b32_e32 v17, v129
	v_mov_b32_e32 v18, v129
	v_mov_b32_e32 v19, v129
	v_mov_b32_e32 v20, v129
	v_mov_b32_e32 v21, v129
	v_mov_b32_e32 v22, v129
	v_mov_b32_e32 v23, v129
	v_mov_b32_e32 v24, v129
	v_mov_b32_e32 v25, v129
	v_mov_b32_e32 v26, v129
	v_mov_b32_e32 v27, v129
	v_mov_b32_e32 v28, v129
	v_mov_b32_e32 v29, v129
	v_mov_b32_e32 v30, v129
	v_mov_b32_e32 v31, v129
	v_mov_b32_e32 v32, 0
	v_mov_b32_e32 v33, v129
	v_mov_b32_e32 v34, v129
	v_mov_b32_e32 v35, v129
	v_mov_b32_e32 v36, v129
	v_mov_b32_e32 v37, v129
	v_mov_b32_e32 v38, v129
	v_mov_b32_e32 v39, v129
	v_mov_b32_e32 v40, v129
	v_mov_b32_e32 v41, v129
	v_mov_b32_e32 v42, v129
	v_mov_b32_e32 v43, v129
	v_mov_b32_e32 v44, v129
	v_mov_b32_e32 v45, v129
	v_mov_b32_e32 v46, v129
	v_mov_b32_e32 v47, v129
	v_mov_b32_e32 v48, 0
	v_mov_b32_e32 v49, v129
	v_mov_b32_e32 v50, v129
	v_mov_b32_e32 v51, v129
	v_mov_b32_e32 v52, v129
	v_mov_b32_e32 v53, v129
	v_mov_b32_e32 v54, v129
	v_mov_b32_e32 v55, v129
	v_mov_b32_e32 v56, v129
	v_mov_b32_e32 v57, v129
	v_mov_b32_e32 v58, v129
	v_mov_b32_e32 v59, v129
	v_mov_b32_e32 v60, v129
	v_mov_b32_e32 v61, v129
	v_mov_b32_e32 v62, v129
	v_mov_b32_e32 v63, v129
	v_mov_b32_e32 v64, 0
	v_mov_b32_e32 v65, v129
	v_mov_b32_e32 v66, v129
	v_mov_b32_e32 v67, v129
	v_mov_b32_e32 v68, v129
	v_mov_b32_e32 v69, v129
	v_mov_b32_e32 v70, v129
	v_mov_b32_e32 v71, v129
	v_mov_b32_e32 v72, v129
	v_mov_b32_e32 v73, v129
	v_mov_b32_e32 v74, v129
	v_mov_b32_e32 v75, v129
	v_mov_b32_e32 v76, v129
	v_mov_b32_e32 v77, v129
	v_mov_b32_e32 v78, v129
	v_mov_b32_e32 v79, v129
	v_mov_b32_e32 v80, 0
	v_mov_b32_e32 v81, v129
	v_mov_b32_e32 v82, v129
	v_mov_b32_e32 v83, v129
	v_mov_b32_e32 v84, v129
	v_mov_b32_e32 v85, v129
	v_mov_b32_e32 v86, v129
	v_mov_b32_e32 v87, v129
	v_mov_b32_e32 v88, v129
	v_mov_b32_e32 v89, v129
	v_mov_b32_e32 v90, v129
	v_mov_b32_e32 v91, v129
	v_mov_b32_e32 v92, v129
	v_mov_b32_e32 v93, v129
	v_mov_b32_e32 v94, v129
	v_mov_b32_e32 v95, v129
	v_mov_b32_e32 v96, 0
	v_mov_b32_e32 v97, v129
	v_mov_b32_e32 v98, v129
	v_mov_b32_e32 v99, v129
	v_mov_b32_e32 v100, v129
	v_mov_b32_e32 v101, v129
	v_mov_b32_e32 v102, v129
	v_mov_b32_e32 v103, v129
	v_mov_b32_e32 v104, v129
	v_mov_b32_e32 v105, v129
	v_mov_b32_e32 v106, v129
	v_mov_b32_e32 v107, v129
	v_mov_b32_e32 v108, v129
	v_mov_b32_e32 v109, v129
	v_mov_b32_e32 v110, v129
	v_mov_b32_e32 v111, v129
	v_mov_b32_e32 v112, 0
	v_mov_b32_e32 v113, v129
	v_mov_b32_e32 v114, v129
	v_mov_b32_e32 v115, v129
	v_mov_b32_e32 v116, v129
	v_mov_b32_e32 v117, v129
	v_mov_b32_e32 v118, v129
	v_mov_b32_e32 v119, v129
	v_mov_b32_e32 v120, v129
	v_mov_b32_e32 v121, v129
	v_mov_b32_e32 v122, v129
	v_mov_b32_e32 v123, v129
	v_mov_b32_e32 v124, v129
	v_mov_b32_e32 v125, v129
	v_mov_b32_e32 v126, v129
	v_mov_b32_e32 v127, v129
	s_waitcnt vmcnt(0) lgkmcnt(0)
	s_barrier
	v_readfirstlane_b32 s48, v143
	s_sub_u32 s48, s48, 16
	s_mov_b32 s49, 0
	s_mov_b32 s50, 0x8000
	s_mov_b32 s52, 0x10000
	v_and_b32_e32 v249, 63, v186
	v_and_b32_e32 v250, 15, v249
	v_lshrrev_b32_e32 v245, 4, v249
	v_bfe_u32 v246, v249, 1, 3
	v_xor_b32_e32 v240, v245, v246
	v_or_b32_e32 v245, 4, v245
	v_xor_b32_e32 v241, v245, v246
	v_lshlrev_b32_e32 v240, 4, v240
	v_lshlrev_b32_e32 v241, 4, v241
	v_lshl_add_u32 v240, v250, 7, v240
	v_lshl_add_u32 v241, v250, 7, v241
	v_bfe_u32 v245, v186, 6, 2
	v_lshl_add_u32 v243, v245, 13, v240
	v_lshl_add_u32 v244, v245, 13, v241
	v_lshrrev_b32_e32 v245, 8, v186
	v_lshl_add_u32 v240, v245, 14, v240
	v_lshl_add_u32 v241, v245, 14, v241
	v_readfirstlane_b32 s56, v138
	v_readfirstlane_b32 s57, v139
	s_and_b32 s53, s48, 0x400
	s_lshr_b32 s53, s53, 4
	s_sub_u32 s56, s56, s53
	s_subb_u32 s57, s57, 0
	v_subrev_u32_e32 v247, s56, v138
	s_add_u32 s62, s56, s24
	s_addc_u32 s63, s57, s25
	s_add_u32 s60, s56, s22
	s_addc_u32 s61, s57, s23
	s_add_u32 s58, s56, s20
	s_addc_u32 s59, s57, s21
	s_add_u32 s56, s56, s18
	s_addc_u32 s57, s57, s19
	v_readfirstlane_b32 s64, v140
	v_readfirstlane_b32 s65, v141
	s_and_b32 s53, s48, 0x400
	s_lshr_b32 s53, s53, 4
	s_sub_u32 s64, s64, s53
	s_subb_u32 s65, s65, 0
	v_subrev_u32_e32 v248, s64, v140
	s_add_u32 s70, s64, s24
	s_addc_u32 s71, s65, s25
	s_add_u32 s68, s64, s22
	s_addc_u32 s69, s65, s23
	s_add_u32 s66, s64, s20
	s_addc_u32 s67, s65, s21
	s_add_u32 s64, s64, s18
	s_addc_u32 s65, s65, s19
	s_add_u32 m0, s52, s48
	s_nop 0
	global_load_lds_dwordx4 v247, s[56:57]
	s_add_u32 s56, s56, 0x80
	s_addc_u32 s57, s57, 0
	s_add_u32 s53, s52, s48
	s_add_u32 m0, s53, 0x2000
	s_nop 0
	global_load_lds_dwordx4 v247, s[58:59]
	s_add_u32 s58, s58, 0x80
	s_addc_u32 s59, s59, 0
	s_add_u32 s53, s52, s48
	s_add_u32 m0, s53, 0x4000
	s_nop 0
	global_load_lds_dwordx4 v247, s[60:61]
	s_add_u32 s60, s60, 0x80
	s_addc_u32 s61, s61, 0
	s_add_u32 s53, s52, s48
	s_add_u32 m0, s53, 0x6000
	s_nop 0
	global_load_lds_dwordx4 v247, s[62:63]
	s_add_u32 s62, s62, 0x80
	s_addc_u32 s63, s63, 0
	s_add_u32 s51, s50, 0x10000
	s_sub_u32 s53, s51, 0x28000
	s_cmp_ge_u32 s51, 0x28000
	s_cselect_b32 s51, s53, s51
	s_add_u32 m0, s51, s48
	s_nop 0
	global_load_lds_dwordx4 v248, s[64:65]
	s_add_u32 s64, s64, 0x80
	s_addc_u32 s65, s65, 0
	s_add_u32 s53, s51, s48
	s_add_u32 m0, s53, 0x2000
	s_nop 0
	global_load_lds_dwordx4 v248, s[66:67]
	s_add_u32 s66, s66, 0x80
	s_addc_u32 s67, s67, 0
	s_add_u32 s53, s51, s48
	s_add_u32 m0, s53, 0x4000
	s_nop 0
	global_load_lds_dwordx4 v248, s[68:69]
	s_add_u32 s68, s68, 0x80
	s_addc_u32 s69, s69, 0
	s_add_u32 s53, s51, s48
	s_add_u32 m0, s53, 0x6000
	s_nop 0
	global_load_lds_dwordx4 v248, s[70:71]
	s_add_u32 s70, s70, 0x80
	s_addc_u32 s71, s71, 0
	v_add_u32_e32 v246, s50, v243
	v_add_u32_e32 v245, s49, v240
	ds_read_b128 v[192:195], v246
	ds_read_b128 v[196:199], v246 offset:2048
	ds_read_b128 v[200:203], v246 offset:4096
	ds_read_b128 v[204:207], v246 offset:6144
	ds_read_b128 v[224:227], v245
	ds_read_b128 v[228:231], v245 offset:2048
	ds_read_b128 v[232:235], v245 offset:4096
	ds_read_b128 v[236:239], v245 offset:6144
	.p2align 6
.Lg163_loop:
	s_add_u32 s51, s50, 0x10000
	s_sub_u32 s53, s51, 0x28000
	s_cmp_ge_u32 s51, 0x28000
	s_cselect_b32 s51, s53, s51
	s_add_u32 s52, s49, 0x20000
	s_sub_u32 s53, s52, 0x28000
	s_cmp_ge_u32 s52, 0x28000
	s_cselect_b32 s52, s53, s52
	v_add_u32_e32 v246, s50, v244
	s_waitcnt lgkmcnt(4)
	s_waitcnt lgkmcnt(3)
	v_mfma_f32_16x16x32_bf16 v[112:115], v[192:195], v[224:227], v[112:115]
	v_mfma_f32_16x16x32_bf16 v[120:123], v[196:199], v[224:227], v[120:123]
	v_mfma_f32_16x16x32_bf16 v[96:99], v[200:203], v[224:227], v[96:99]
	v_mfma_f32_16x16x32_bf16 v[104:107], v[204:207], v[224:227], v[104:107]
	s_add_u32 m0, s52, s48
	s_nop 0
	global_load_lds_dwordx4 v247, s[56:57]
	s_add_u32 s56, s56, 0x80
	s_addc_u32 s57, s57, 0
	s_add_u32 s53, s52, s48
	s_add_u32 m0, s53, 0x2000
	s_nop 0
	global_load_lds_dwordx4 v247, s[58:59]
	s_add_u32 s58, s58, 0x80
	s_addc_u32 s59, s59, 0
	ds_read_b128 v[224:227], v245 offset:8192
	ds_read_b128 v[208:211], v246
	s_waitcnt lgkmcnt(4)
	v_mfma_f32_16x16x32_bf16 v[116:119], v[192:195], v[228:231], v[116:119]
	v_mfma_f32_16x16x32_bf16 v[124:127], v[196:199], v[228:231], v[124:127]
	v_mfma_f32_16x16x32_bf16 v[100:103], v[200:203], v[228:231], v[100:103]
	v_mfma_f32_16x16x32_bf16 v[108:111], v[204:207], v[228:231], v[108:111]
	s_add_u32 s53, s52, s48
	s_add_u32 m0, s53, 0x4000
	s_nop 0
	global_load_lds_dwordx4 v247, s[60:61]
	s_add_u32 s60, s60, 0x80
	s_addc_u32 s61, s61, 0
	s_add_u32 s53, s52, s48
	s_add_u32 m0, s53, 0x6000
	s_nop 0
	global_load_lds_dwordx4 v247, s[62:63]
	s_add_u32 s62, s62, 0x80
	s_addc_u32 s63, s63, 0
	ds_read_b128 v[228:231], v245 offset:10240
	ds_read_b128 v[212:215], v246 offset:2048
	s_waitcnt lgkmcnt(5)
	v_mfma_f32_16x16x32_bf16 v[80:83], v[192:195], v[232:235], v[80:83]
	v_mfma_f32_16x16x32_bf16 v[88:91], v[196:199], v[232:235], v[88:91]
	v_mfma_f32_16x16x32_bf16 v[64:67], v[200:203], v[232:235], v[64:67]
	v_mfma_f32_16x16x32_bf16 v[72:75], v[204:207], v[232:235], v[72:75]
	ds_read_b128 v[232:235], v245 offset:12288
	ds_read_b128 v[216:219], v246 offset:4096
	s_waitcnt lgkmcnt(6)
	v_mfma_f32_16x16x32_bf16 v[84:87], v[192:195], v[236:239], v[84:87]
	v_mfma_f32_16x16x32_bf16 v[92:95], v[196:199], v[236:239], v[92:95]
	v_mfma_f32_16x16x32_bf16 v[68:71], v[200:203], v[236:239], v[68:71]
	v_mfma_f32_16x16x32_bf16 v[76:79], v[204:207], v[236:239], v[76:79]
	ds_read_b128 v[236:239], v245 offset:14336
	ds_read_b128 v[220:223], v246 offset:6144
	v_add_u32_e32 v245, s49, v241
	s_waitcnt lgkmcnt(7)
	v_mfma_f32_16x16x32_bf16 v[48:51], v[192:195], v[224:227], v[48:51]
	v_mfma_f32_16x16x32_bf16 v[56:59], v[196:199], v[224:227], v[56:59]
	v_mfma_f32_16x16x32_bf16 v[32:35], v[200:203], v[224:227], v[32:35]
	v_mfma_f32_16x16x32_bf16 v[40:43], v[204:207], v[224:227], v[40:43]
	ds_read_b128 v[224:227], v245
	s_waitcnt lgkmcnt(6)
	v_mfma_f32_16x16x32_bf16 v[52:55], v[192:195], v[228:231], v[52:55]
	v_mfma_f32_16x16x32_bf16 v[60:63], v[196:199], v[228:231], v[60:63]
	v_mfma_f32_16x16x32_bf16 v[36:39], v[200:203], v[228:231], v[36:39]
	v_mfma_f32_16x16x32_bf16 v[44:47], v[204:207], v[228:231], v[44:47]
	ds_read_b128 v[228:231], v245 offset:2048
	s_waitcnt lgkmcnt(5)
	v_mfma_f32_16x16x32_bf16 v[16:19], v[192:195], v[232:235], v[16:19]
	v_mfma_f32_16x16x32_bf16 v[24:27], v[196:199], v[232:235], v[24:27]
	v_mfma_f32_16x16x32_bf16 v[0:3], v[200:203], v[232:235], v[0:3]
	v_mfma_f32_16x16x32_bf16 v[8:11], v[204:207], v[232:235], v[8:11]
	ds_read_b128 v[232:235], v245 offset:4096
	s_waitcnt lgkmcnt(4)
	v_mfma_f32_16x16x32_bf16 v[20:23], v[192:195], v[236:239], v[20:23]
	v_mfma_f32_16x16x32_bf16 v[28:31], v[196:199], v[236:239], v[28:31]
	v_mfma_f32_16x16x32_bf16 v[4:7], v[200:203], v[236:239], v[4:7]
	v_mfma_f32_16x16x32_bf16 v[12:15], v[204:207], v[236:239], v[12:15]
	ds_read_b128 v[236:239], v245 offset:6144
	s_waitcnt lgkmcnt(4)
	s_waitcnt lgkmcnt(3)
	v_mfma_f32_16x16x32_bf16 v[112:115], v[208:211], v[224:227], v[112:115]
	v_mfma_f32_16x16x32_bf16 v[120:123], v[212:215], v[224:227], v[120:123]
	v_mfma_f32_16x16x32_bf16 v[96:99], v[216:219], v[224:227], v[96:99]
	v_mfma_f32_16x16x32_bf16 v[104:107], v[220:223], v[224:227], v[104:107]
	ds_read_b128 v[224:227], v245 offset:8192
	s_waitcnt lgkmcnt(3)
	v_mfma_f32_16x16x32_bf16 v[116:119], v[208:211], v[228:231], v[116:119]
	v_mfma_f32_16x16x32_bf16 v[124:127], v[212:215], v[228:231], v[124:127]
	v_mfma_f32_16x16x32_bf16 v[100:103], v[216:219], v[228:231], v[100:103]
	v_mfma_f32_16x16x32_bf16 v[108:111], v[220:223], v[228:231], v[108:111]
	ds_read_b128 v[228:231], v245 offset:10240
	s_waitcnt lgkmcnt(3)
	v_mfma_f32_16x16x32_bf16 v[80:83], v[208:211], v[232:235], v[80:83]
	v_mfma_f32_16x16x32_bf16 v[88:91], v[212:215], v[232:235], v[88:91]
	v_mfma_f32_16x16x32_bf16 v[64:67], v[216:219], v[232:235], v[64:67]
	v_mfma_f32_16x16x32_bf16 v[72:75], v[220:223], v[232:235], v[72:75]
	ds_read_b128 v[232:235], v245 offset:12288
	s_waitcnt lgkmcnt(3)
	v_mfma_f32_16x16x32_bf16 v[84:87], v[208:211], v[236:239], v[84:87]
	v_mfma_f32_16x16x32_bf16 v[92:95], v[212:215], v[236:239], v[92:95]
	v_mfma_f32_16x16x32_bf16 v[68:71], v[216:219], v[236:239], v[68:71]
	v_mfma_f32_16x16x32_bf16 v[76:79], v[220:223], v[236:239], v[76:79]
	ds_read_b128 v[236:239], v245 offset:14336
	s_waitcnt lgkmcnt(3)
	v_mfma_f32_16x16x32_bf16 v[48:51], v[208:211], v[224:227], v[48:51]
	v_mfma_f32_16x16x32_bf16 v[56:59], v[212:215], v[224:227], v[56:59]
	v_mfma_f32_16x16x32_bf16 v[32:35], v[216:219], v[224:227], v[32:35]
	v_mfma_f32_16x16x32_bf16 v[40:43], v[220:223], v[224:227], v[40:43]
	s_waitcnt lgkmcnt(2)
	v_mfma_f32_16x16x32_bf16 v[52:55], v[208:211], v[228:231], v[52:55]
	v_mfma_f32_16x16x32_bf16 v[60:63], v[212:215], v[228:231], v[60:63]
	v_mfma_f32_16x16x32_bf16 v[36:39], v[216:219], v[228:231], v[36:39]
	v_mfma_f32_16x16x32_bf16 v[44:47], v[220:223], v[228:231], v[44:47]
	s_waitcnt lgkmcnt(1)
	v_mfma_f32_16x16x32_bf16 v[16:19], v[208:211], v[232:235], v[16:19]
	v_mfma_f32_16x16x32_bf16 v[24:27], v[212:215], v[232:235], v[24:27]
	v_mfma_f32_16x16x32_bf16 v[0:3], v[216:219], v[232:235], v[0:3]
	v_mfma_f32_16x16x32_bf16 v[8:11], v[220:223], v[232:235], v[8:11]
	s_waitcnt lgkmcnt(0)
	s_add_u32 s28, s28, 0x80
	s_addc_u32 s29, s29, 0
	s_add_u32 s49, s49, 0x10000
	s_sub_u32 s53, s49, 0x28000
	s_cmp_ge_u32 s49, 0x28000
	s_cselect_b32 s49, s53, s49
	s_mov_b32 s50, s51
	s_waitcnt vmcnt(4)
	s_barrier
	v_add_u32_e32 v246, s50, v243
	v_add_u32_e32 v245, s49, v240
	ds_read_b128 v[192:195], v246
	ds_read_b128 v[196:199], v246 offset:2048
	ds_read_b128 v[200:203], v246 offset:4096
	ds_read_b128 v[204:207], v246 offset:6144
	ds_read_b128 v[224:227], v245
	ds_read_b128 v[228:231], v245 offset:2048
	ds_read_b128 v[232:235], v245 offset:4096
	s_add_u32 s51, s50, 0x10000
	s_sub_u32 s53, s51, 0x28000
	s_cmp_ge_u32 s51, 0x28000
	s_cselect_b32 s51, s53, s51
	s_add_u32 m0, s51, s48
	s_nop 0
	global_load_lds_dwordx4 v248, s[64:65]
	s_add_u32 s64, s64, 0x80
	s_addc_u32 s65, s65, 0
	s_add_u32 s53, s51, s48
	s_add_u32 m0, s53, 0x2000
	s_nop 0
	global_load_lds_dwordx4 v248, s[66:67]
	s_add_u32 s66, s66, 0x80
	s_addc_u32 s67, s67, 0
	s_add_u32 s53, s51, s48
	s_add_u32 m0, s53, 0x4000
	s_nop 0
	global_load_lds_dwordx4 v248, s[68:69]
	s_add_u32 s68, s68, 0x80
	s_addc_u32 s69, s69, 0
	s_add_u32 s53, s51, s48
	s_add_u32 m0, s53, 0x6000
	s_nop 0
	global_load_lds_dwordx4 v248, s[70:71]
	s_add_u32 s70, s70, 0x80
	s_addc_u32 s71, s71, 0
	v_mfma_f32_16x16x32_bf16 v[20:23], v[208:211], v[236:239], v[20:23]
	v_mfma_f32_16x16x32_bf16 v[28:31], v[212:215], v[236:239], v[28:31]
	v_mfma_f32_16x16x32_bf16 v[4:7], v[216:219], v[236:239], v[4:7]
	v_mfma_f32_16x16x32_bf16 v[12:15], v[220:223], v[236:239], v[12:15]
	ds_read_b128 v[236:239], v245 offset:6144
	s_cmpk_lg_i32 s28, 0xf00
	s_cbranch_scc1 .Lg163_loop
	s_add_u32 s51, s50, 0x10000
	s_sub_u32 s53, s51, 0x28000
	s_cmp_ge_u32 s51, 0x28000
	s_cselect_b32 s51, s53, s51
	v_add_u32_e32 v246, s50, v244
	s_waitcnt lgkmcnt(4)
	s_waitcnt lgkmcnt(3)
	v_mfma_f32_16x16x32_bf16 v[112:115], v[192:195], v[224:227], v[112:115]
	v_mfma_f32_16x16x32_bf16 v[120:123], v[196:199], v[224:227], v[120:123]
	v_mfma_f32_16x16x32_bf16 v[96:99], v[200:203], v[224:227], v[96:99]
	v_mfma_f32_16x16x32_bf16 v[104:107], v[204:207], v[224:227], v[104:107]
	ds_read_b128 v[224:227], v245 offset:8192
	ds_read_b128 v[208:211], v246
	s_waitcnt lgkmcnt(4)
	v_mfma_f32_16x16x32_bf16 v[116:119], v[192:195], v[228:231], v[116:119]
	v_mfma_f32_16x16x32_bf16 v[124:127], v[196:199], v[228:231], v[124:127]
	v_mfma_f32_16x16x32_bf16 v[100:103], v[200:203], v[228:231], v[100:103]
	v_mfma_f32_16x16x32_bf16 v[108:111], v[204:207], v[228:231], v[108:111]
	ds_read_b128 v[228:231], v245 offset:10240
	ds_read_b128 v[212:215], v246 offset:2048
	s_waitcnt lgkmcnt(5)
	v_mfma_f32_16x16x32_bf16 v[80:83], v[192:195], v[232:235], v[80:83]
	v_mfma_f32_16x16x32_bf16 v[88:91], v[196:199], v[232:235], v[88:91]
	v_mfma_f32_16x16x32_bf16 v[64:67], v[200:203], v[232:235], v[64:67]
	v_mfma_f32_16x16x32_bf16 v[72:75], v[204:207], v[232:235], v[72:75]
	ds_read_b128 v[232:235], v245 offset:12288
	ds_read_b128 v[216:219], v246 offset:4096
	s_waitcnt lgkmcnt(6)
	v_mfma_f32_16x16x32_bf16 v[84:87], v[192:195], v[236:239], v[84:87]
	v_mfma_f32_16x16x32_bf16 v[92:95], v[196:199], v[236:239], v[92:95]
	v_mfma_f32_16x16x32_bf16 v[68:71], v[200:203], v[236:239], v[68:71]
	v_mfma_f32_16x16x32_bf16 v[76:79], v[204:207], v[236:239], v[76:79]
	ds_read_b128 v[236:239], v245 offset:14336
	ds_read_b128 v[220:223], v246 offset:6144
	v_add_u32_e32 v245, s49, v241
	s_waitcnt lgkmcnt(7)
	v_mfma_f32_16x16x32_bf16 v[48:51], v[192:195], v[224:227], v[48:51]
	v_mfma_f32_16x16x32_bf16 v[56:59], v[196:199], v[224:227], v[56:59]
	v_mfma_f32_16x16x32_bf16 v[32:35], v[200:203], v[224:227], v[32:35]
	v_mfma_f32_16x16x32_bf16 v[40:43], v[204:207], v[224:227], v[40:43]
	ds_read_b128 v[224:227], v245
	s_waitcnt lgkmcnt(6)
	v_mfma_f32_16x16x32_bf16 v[52:55], v[192:195], v[228:231], v[52:55]
	v_mfma_f32_16x16x32_bf16 v[60:63], v[196:199], v[228:231], v[60:63]
	v_mfma_f32_16x16x32_bf16 v[36:39], v[200:203], v[228:231], v[36:39]
	v_mfma_f32_16x16x32_bf16 v[44:47], v[204:207], v[228:231], v[44:47]
	ds_read_b128 v[228:231], v245 offset:2048
	s_waitcnt lgkmcnt(5)
	v_mfma_f32_16x16x32_bf16 v[16:19], v[192:195], v[232:235], v[16:19]
	v_mfma_f32_16x16x32_bf16 v[24:27], v[196:199], v[232:235], v[24:27]
	v_mfma_f32_16x16x32_bf16 v[0:3], v[200:203], v[232:235], v[0:3]
	v_mfma_f32_16x16x32_bf16 v[8:11], v[204:207], v[232:235], v[8:11]
	ds_read_b128 v[232:235], v245 offset:4096
	s_waitcnt lgkmcnt(4)
	v_mfma_f32_16x16x32_bf16 v[20:23], v[192:195], v[236:239], v[20:23]
	v_mfma_f32_16x16x32_bf16 v[28:31], v[196:199], v[236:239], v[28:31]
	v_mfma_f32_16x16x32_bf16 v[4:7], v[200:203], v[236:239], v[4:7]
	v_mfma_f32_16x16x32_bf16 v[12:15], v[204:207], v[236:239], v[12:15]
	ds_read_b128 v[236:239], v245 offset:6144
	s_waitcnt lgkmcnt(4)
	s_waitcnt lgkmcnt(3)
	v_mfma_f32_16x16x32_bf16 v[112:115], v[208:211], v[224:227], v[112:115]
	v_mfma_f32_16x16x32_bf16 v[120:123], v[212:215], v[224:227], v[120:123]
	v_mfma_f32_16x16x32_bf16 v[96:99], v[216:219], v[224:227], v[96:99]
	v_mfma_f32_16x16x32_bf16 v[104:107], v[220:223], v[224:227], v[104:107]
	ds_read_b128 v[224:227], v245 offset:8192
	s_waitcnt lgkmcnt(3)
	v_mfma_f32_16x16x32_bf16 v[116:119], v[208:211], v[228:231], v[116:119]
	v_mfma_f32_16x16x32_bf16 v[124:127], v[212:215], v[228:231], v[124:127]
	v_mfma_f32_16x16x32_bf16 v[100:103], v[216:219], v[228:231], v[100:103]
	v_mfma_f32_16x16x32_bf16 v[108:111], v[220:223], v[228:231], v[108:111]
	ds_read_b128 v[228:231], v245 offset:10240
	s_waitcnt lgkmcnt(3)
	v_mfma_f32_16x16x32_bf16 v[80:83], v[208:211], v[232:235], v[80:83]
	v_mfma_f32_16x16x32_bf16 v[88:91], v[212:215], v[232:235], v[88:91]
	v_mfma_f32_16x16x32_bf16 v[64:67], v[216:219], v[232:235], v[64:67]
	v_mfma_f32_16x16x32_bf16 v[72:75], v[220:223], v[232:235], v[72:75]
	ds_read_b128 v[232:235], v245 offset:12288
	s_waitcnt lgkmcnt(3)
	v_mfma_f32_16x16x32_bf16 v[84:87], v[208:211], v[236:239], v[84:87]
	v_mfma_f32_16x16x32_bf16 v[92:95], v[212:215], v[236:239], v[92:95]
	v_mfma_f32_16x16x32_bf16 v[68:71], v[216:219], v[236:239], v[68:71]
	v_mfma_f32_16x16x32_bf16 v[76:79], v[220:223], v[236:239], v[76:79]
	ds_read_b128 v[236:239], v245 offset:14336
	s_waitcnt lgkmcnt(3)
	v_mfma_f32_16x16x32_bf16 v[48:51], v[208:211], v[224:227], v[48:51]
	v_mfma_f32_16x16x32_bf16 v[56:59], v[212:215], v[224:227], v[56:59]
	v_mfma_f32_16x16x32_bf16 v[32:35], v[216:219], v[224:227], v[32:35]
	v_mfma_f32_16x16x32_bf16 v[40:43], v[220:223], v[224:227], v[40:43]
	s_waitcnt lgkmcnt(2)
	v_mfma_f32_16x16x32_bf16 v[52:55], v[208:211], v[228:231], v[52:55]
	v_mfma_f32_16x16x32_bf16 v[60:63], v[212:215], v[228:231], v[60:63]
	v_mfma_f32_16x16x32_bf16 v[36:39], v[216:219], v[228:231], v[36:39]
	v_mfma_f32_16x16x32_bf16 v[44:47], v[220:223], v[228:231], v[44:47]
	s_waitcnt lgkmcnt(1)
	v_mfma_f32_16x16x32_bf16 v[16:19], v[208:211], v[232:235], v[16:19]
	v_mfma_f32_16x16x32_bf16 v[24:27], v[212:215], v[232:235], v[24:27]
	v_mfma_f32_16x16x32_bf16 v[0:3], v[216:219], v[232:235], v[0:3]
	v_mfma_f32_16x16x32_bf16 v[8:11], v[220:223], v[232:235], v[8:11]
	s_waitcnt lgkmcnt(0)
	s_add_u32 s28, s28, 0x80
	s_addc_u32 s29, s29, 0
	s_add_u32 s49, s49, 0x10000
	s_sub_u32 s53, s49, 0x28000
	s_cmp_ge_u32 s49, 0x28000
	s_cselect_b32 s49, s53, s49
	s_mov_b32 s50, s51
	s_waitcnt vmcnt(0)
	s_barrier
	v_add_u32_e32 v246, s50, v243
	v_add_u32_e32 v245, s49, v240
	ds_read_b128 v[192:195], v246
	ds_read_b128 v[196:199], v246 offset:2048
	ds_read_b128 v[200:203], v246 offset:4096
	ds_read_b128 v[204:207], v246 offset:6144
	ds_read_b128 v[224:227], v245
	ds_read_b128 v[228:231], v245 offset:2048
	ds_read_b128 v[232:235], v245 offset:4096
	v_mfma_f32_16x16x32_bf16 v[20:23], v[208:211], v[236:239], v[20:23]
	v_mfma_f32_16x16x32_bf16 v[28:31], v[212:215], v[236:239], v[28:31]
	v_mfma_f32_16x16x32_bf16 v[4:7], v[216:219], v[236:239], v[4:7]
	v_mfma_f32_16x16x32_bf16 v[12:15], v[220:223], v[236:239], v[12:15]
	ds_read_b128 v[236:239], v245 offset:6144
	v_add_u32_e32 v246, s50, v244
	s_waitcnt lgkmcnt(4)
	s_waitcnt lgkmcnt(3)
	v_mfma_f32_16x16x32_bf16 v[112:115], v[192:195], v[224:227], v[112:115]
	v_mfma_f32_16x16x32_bf16 v[120:123], v[196:199], v[224:227], v[120:123]
	v_mfma_f32_16x16x32_bf16 v[96:99], v[200:203], v[224:227], v[96:99]
	v_mfma_f32_16x16x32_bf16 v[104:107], v[204:207], v[224:227], v[104:107]
	ds_read_b128 v[224:227], v245 offset:8192
	ds_read_b128 v[208:211], v246
	s_waitcnt lgkmcnt(4)
	v_mfma_f32_16x16x32_bf16 v[116:119], v[192:195], v[228:231], v[116:119]
	v_mfma_f32_16x16x32_bf16 v[124:127], v[196:199], v[228:231], v[124:127]
	v_mfma_f32_16x16x32_bf16 v[100:103], v[200:203], v[228:231], v[100:103]
	v_mfma_f32_16x16x32_bf16 v[108:111], v[204:207], v[228:231], v[108:111]
	ds_read_b128 v[228:231], v245 offset:10240
	ds_read_b128 v[212:215], v246 offset:2048
	s_waitcnt lgkmcnt(5)
	v_mfma_f32_16x16x32_bf16 v[80:83], v[192:195], v[232:235], v[80:83]
	v_mfma_f32_16x16x32_bf16 v[88:91], v[196:199], v[232:235], v[88:91]
	v_mfma_f32_16x16x32_bf16 v[64:67], v[200:203], v[232:235], v[64:67]
	v_mfma_f32_16x16x32_bf16 v[72:75], v[204:207], v[232:235], v[72:75]
	ds_read_b128 v[232:235], v245 offset:12288
	ds_read_b128 v[216:219], v246 offset:4096
	s_waitcnt lgkmcnt(6)
	v_mfma_f32_16x16x32_bf16 v[84:87], v[192:195], v[236:239], v[84:87]
	v_mfma_f32_16x16x32_bf16 v[92:95], v[196:199], v[236:239], v[92:95]
	v_mfma_f32_16x16x32_bf16 v[68:71], v[200:203], v[236:239], v[68:71]
	v_mfma_f32_16x16x32_bf16 v[76:79], v[204:207], v[236:239], v[76:79]
	ds_read_b128 v[236:239], v245 offset:14336
	ds_read_b128 v[220:223], v246 offset:6144
	v_add_u32_e32 v245, s49, v241
	s_waitcnt lgkmcnt(7)
	v_mfma_f32_16x16x32_bf16 v[48:51], v[192:195], v[224:227], v[48:51]
	v_mfma_f32_16x16x32_bf16 v[56:59], v[196:199], v[224:227], v[56:59]
	v_mfma_f32_16x16x32_bf16 v[32:35], v[200:203], v[224:227], v[32:35]
	v_mfma_f32_16x16x32_bf16 v[40:43], v[204:207], v[224:227], v[40:43]
	ds_read_b128 v[224:227], v245
	s_waitcnt lgkmcnt(6)
	v_mfma_f32_16x16x32_bf16 v[52:55], v[192:195], v[228:231], v[52:55]
	v_mfma_f32_16x16x32_bf16 v[60:63], v[196:199], v[228:231], v[60:63]
	v_mfma_f32_16x16x32_bf16 v[36:39], v[200:203], v[228:231], v[36:39]
	v_mfma_f32_16x16x32_bf16 v[44:47], v[204:207], v[228:231], v[44:47]
	ds_read_b128 v[228:231], v245 offset:2048
	s_waitcnt lgkmcnt(5)
	v_mfma_f32_16x16x32_bf16 v[16:19], v[192:195], v[232:235], v[16:19]
	v_mfma_f32_16x16x32_bf16 v[24:27], v[196:199], v[232:235], v[24:27]
	v_mfma_f32_16x16x32_bf16 v[0:3], v[200:203], v[232:235], v[0:3]
	v_mfma_f32_16x16x32_bf16 v[8:11], v[204:207], v[232:235], v[8:11]
	ds_read_b128 v[232:235], v245 offset:4096
	s_waitcnt lgkmcnt(4)
	v_mfma_f32_16x16x32_bf16 v[20:23], v[192:195], v[236:239], v[20:23]
	v_mfma_f32_16x16x32_bf16 v[28:31], v[196:199], v[236:239], v[28:31]
	v_mfma_f32_16x16x32_bf16 v[4:7], v[200:203], v[236:239], v[4:7]
	v_mfma_f32_16x16x32_bf16 v[12:15], v[204:207], v[236:239], v[12:15]
	ds_read_b128 v[236:239], v245 offset:6144
	s_waitcnt lgkmcnt(4)
	s_waitcnt lgkmcnt(3)
	v_mfma_f32_16x16x32_bf16 v[112:115], v[208:211], v[224:227], v[112:115]
	v_mfma_f32_16x16x32_bf16 v[120:123], v[212:215], v[224:227], v[120:123]
	v_mfma_f32_16x16x32_bf16 v[96:99], v[216:219], v[224:227], v[96:99]
	v_mfma_f32_16x16x32_bf16 v[104:107], v[220:223], v[224:227], v[104:107]
	ds_read_b128 v[224:227], v245 offset:8192
	s_waitcnt lgkmcnt(3)
	v_mfma_f32_16x16x32_bf16 v[116:119], v[208:211], v[228:231], v[116:119]
	v_mfma_f32_16x16x32_bf16 v[124:127], v[212:215], v[228:231], v[124:127]
	v_mfma_f32_16x16x32_bf16 v[100:103], v[216:219], v[228:231], v[100:103]
	v_mfma_f32_16x16x32_bf16 v[108:111], v[220:223], v[228:231], v[108:111]
	ds_read_b128 v[228:231], v245 offset:10240
	s_waitcnt lgkmcnt(3)
	v_mfma_f32_16x16x32_bf16 v[80:83], v[208:211], v[232:235], v[80:83]
	v_mfma_f32_16x16x32_bf16 v[88:91], v[212:215], v[232:235], v[88:91]
	v_mfma_f32_16x16x32_bf16 v[64:67], v[216:219], v[232:235], v[64:67]
	v_mfma_f32_16x16x32_bf16 v[72:75], v[220:223], v[232:235], v[72:75]
	ds_read_b128 v[232:235], v245 offset:12288
	s_waitcnt lgkmcnt(3)
	v_mfma_f32_16x16x32_bf16 v[84:87], v[208:211], v[236:239], v[84:87]
	v_mfma_f32_16x16x32_bf16 v[92:95], v[212:215], v[236:239], v[92:95]
	v_mfma_f32_16x16x32_bf16 v[68:71], v[216:219], v[236:239], v[68:71]
	v_mfma_f32_16x16x32_bf16 v[76:79], v[220:223], v[236:239], v[76:79]
	ds_read_b128 v[236:239], v245 offset:14336
	s_waitcnt lgkmcnt(3)
	v_mfma_f32_16x16x32_bf16 v[48:51], v[208:211], v[224:227], v[48:51]
	v_mfma_f32_16x16x32_bf16 v[56:59], v[212:215], v[224:227], v[56:59]
	v_mfma_f32_16x16x32_bf16 v[32:35], v[216:219], v[224:227], v[32:35]
	v_mfma_f32_16x16x32_bf16 v[40:43], v[220:223], v[224:227], v[40:43]
	s_waitcnt lgkmcnt(2)
	v_mfma_f32_16x16x32_bf16 v[52:55], v[208:211], v[228:231], v[52:55]
	v_mfma_f32_16x16x32_bf16 v[60:63], v[212:215], v[228:231], v[60:63]
	v_mfma_f32_16x16x32_bf16 v[36:39], v[216:219], v[228:231], v[36:39]
	v_mfma_f32_16x16x32_bf16 v[44:47], v[220:223], v[228:231], v[44:47]
	s_waitcnt lgkmcnt(1)
	v_mfma_f32_16x16x32_bf16 v[16:19], v[208:211], v[232:235], v[16:19]
	v_mfma_f32_16x16x32_bf16 v[24:27], v[212:215], v[232:235], v[24:27]
	v_mfma_f32_16x16x32_bf16 v[0:3], v[216:219], v[232:235], v[0:3]
	v_mfma_f32_16x16x32_bf16 v[8:11], v[220:223], v[232:235], v[8:11]
	s_waitcnt lgkmcnt(0)
	s_waitcnt vmcnt(0)
	s_barrier
	v_mfma_f32_16x16x32_bf16 v[20:23], v[208:211], v[236:239], v[20:23]
	v_mfma_f32_16x16x32_bf16 v[28:31], v[212:215], v[236:239], v[28:31]
	v_mfma_f32_16x16x32_bf16 v[4:7], v[216:219], v[236:239], v[4:7]
	v_mfma_f32_16x16x32_bf16 v[12:15], v[220:223], v[236:239], v[12:15]
	s_nop 15
	v_permlane16_swap_b32_e32 v112, v116
	v_permlane16_swap_b32_e32 v113, v117
	v_permlane16_swap_b32_e32 v114, v118
	v_permlane16_swap_b32_e32 v115, v119
	v_permlane16_swap_b32_e32 v120, v124
	v_permlane16_swap_b32_e32 v121, v125
	v_permlane16_swap_b32_e32 v122, v126
	v_permlane16_swap_b32_e32 v123, v127
	v_permlane16_swap_b32_e32 v96, v100
	v_permlane16_swap_b32_e32 v97, v101
	v_permlane16_swap_b32_e32 v98, v102
	v_permlane16_swap_b32_e32 v99, v103
	v_permlane16_swap_b32_e32 v104, v108
	v_permlane16_swap_b32_e32 v105, v109
	v_permlane16_swap_b32_e32 v106, v110
	v_permlane16_swap_b32_e32 v107, v111
	v_permlane16_swap_b32_e32 v80, v84
	v_permlane16_swap_b32_e32 v81, v85
	v_permlane16_swap_b32_e32 v82, v86
	v_permlane16_swap_b32_e32 v83, v87
	v_permlane16_swap_b32_e32 v88, v92
	v_permlane16_swap_b32_e32 v89, v93
	v_permlane16_swap_b32_e32 v90, v94
	v_permlane16_swap_b32_e32 v91, v95
	v_permlane16_swap_b32_e32 v64, v68
	v_permlane16_swap_b32_e32 v65, v69
	v_permlane16_swap_b32_e32 v66, v70
	v_permlane16_swap_b32_e32 v67, v71
	v_permlane16_swap_b32_e32 v72, v76
	v_permlane16_swap_b32_e32 v73, v77
	v_permlane16_swap_b32_e32 v74, v78
	v_permlane16_swap_b32_e32 v75, v79
	v_permlane16_swap_b32_e32 v48, v52
	v_permlane16_swap_b32_e32 v49, v53
	v_permlane16_swap_b32_e32 v50, v54
	v_permlane16_swap_b32_e32 v51, v55
	v_permlane16_swap_b32_e32 v56, v60
	v_permlane16_swap_b32_e32 v57, v61
	v_permlane16_swap_b32_e32 v58, v62
	v_permlane16_swap_b32_e32 v59, v63
	v_permlane16_swap_b32_e32 v32, v36
	v_permlane16_swap_b32_e32 v33, v37
	v_permlane16_swap_b32_e32 v34, v38
	v_permlane16_swap_b32_e32 v35, v39
	v_permlane16_swap_b32_e32 v40, v44
	v_permlane16_swap_b32_e32 v41, v45
	v_permlane16_swap_b32_e32 v42, v46
	v_permlane16_swap_b32_e32 v43, v47
	v_permlane16_swap_b32_e32 v16, v20
	v_permlane16_swap_b32_e32 v17, v21
	v_permlane16_swap_b32_e32 v18, v22
	v_permlane16_swap_b32_e32 v19, v23
	v_permlane16_swap_b32_e32 v24, v28
	v_permlane16_swap_b32_e32 v25, v29
	v_permlane16_swap_b32_e32 v26, v30
	v_permlane16_swap_b32_e32 v27, v31
	v_permlane16_swap_b32_e32 v0, v4
	v_permlane16_swap_b32_e32 v1, v5
	v_permlane16_swap_b32_e32 v2, v6
	v_permlane16_swap_b32_e32 v3, v7
	v_permlane16_swap_b32_e32 v8, v12
	v_permlane16_swap_b32_e32 v9, v13
	v_permlane16_swap_b32_e32 v10, v14
	v_permlane16_swap_b32_e32 v11, v15
	v_permlane32_swap_b32_e32 v112, v116
	v_permlane32_swap_b32_e32 v113, v117
	v_permlane32_swap_b32_e32 v114, v118
	v_permlane32_swap_b32_e32 v115, v119
	v_permlane32_swap_b32_e32 v120, v124
	v_permlane32_swap_b32_e32 v121, v125
	v_permlane32_swap_b32_e32 v122, v126
	v_permlane32_swap_b32_e32 v123, v127
	v_permlane32_swap_b32_e32 v96, v100
	v_permlane32_swap_b32_e32 v97, v101
	v_permlane32_swap_b32_e32 v98, v102
	v_permlane32_swap_b32_e32 v99, v103
	v_permlane32_swap_b32_e32 v104, v108
	v_permlane32_swap_b32_e32 v105, v109
	v_permlane32_swap_b32_e32 v106, v110
	v_permlane32_swap_b32_e32 v107, v111
	v_permlane32_swap_b32_e32 v80, v84
	v_permlane32_swap_b32_e32 v81, v85
	v_permlane32_swap_b32_e32 v82, v86
	v_permlane32_swap_b32_e32 v83, v87
	v_permlane32_swap_b32_e32 v88, v92
	v_permlane32_swap_b32_e32 v89, v93
	v_permlane32_swap_b32_e32 v90, v94
	v_permlane32_swap_b32_e32 v91, v95
	v_permlane32_swap_b32_e32 v64, v68
	v_permlane32_swap_b32_e32 v65, v69
	v_permlane32_swap_b32_e32 v66, v70
	v_permlane32_swap_b32_e32 v67, v71
	v_permlane32_swap_b32_e32 v72, v76
	v_permlane32_swap_b32_e32 v73, v77
	v_permlane32_swap_b32_e32 v74, v78
	v_permlane32_swap_b32_e32 v75, v79
	v_permlane32_swap_b32_e32 v48, v52
	v_permlane32_swap_b32_e32 v49, v53
	v_permlane32_swap_b32_e32 v50, v54
	v_permlane32_swap_b32_e32 v51, v55
	v_permlane32_swap_b32_e32 v56, v60
	v_permlane32_swap_b32_e32 v57, v61
	v_permlane32_swap_b32_e32 v58, v62
	v_permlane32_swap_b32_e32 v59, v63
	v_permlane32_swap_b32_e32 v32, v36
	v_permlane32_swap_b32_e32 v33, v37
	v_permlane32_swap_b32_e32 v34, v38
	v_permlane32_swap_b32_e32 v35, v39
	v_permlane32_swap_b32_e32 v40, v44
	v_permlane32_swap_b32_e32 v41, v45
	v_permlane32_swap_b32_e32 v42, v46
	v_permlane32_swap_b32_e32 v43, v47
	v_permlane32_swap_b32_e32 v16, v20
	v_permlane32_swap_b32_e32 v17, v21
	v_permlane32_swap_b32_e32 v18, v22
	v_permlane32_swap_b32_e32 v19, v23
	v_permlane32_swap_b32_e32 v24, v28
	v_permlane32_swap_b32_e32 v25, v29
	v_permlane32_swap_b32_e32 v26, v30
	v_permlane32_swap_b32_e32 v27, v31
	v_permlane32_swap_b32_e32 v0, v4
	v_permlane32_swap_b32_e32 v1, v5
	v_permlane32_swap_b32_e32 v2, v6
	v_permlane32_swap_b32_e32 v3, v7
	v_permlane32_swap_b32_e32 v8, v12
	v_permlane32_swap_b32_e32 v9, v13
	v_permlane32_swap_b32_e32 v10, v14
	v_permlane32_swap_b32_e32 v11, v15
	s_nop 1
